# GEMM K-loops: loop-edge SALU (counter/pointer update and next-iteration pointer selects) moved ahead of the loop-back barrier
# baseline (speedup 1.0000x reference)
; #define PG8_STAGE(bufoff, gbase, voff) do { _Pragma("unroll") for (int _i = 0; _i < 2; ++_i) \
;         __builtin_amdgcn_global_load_lds((const unsigned*)((const char*)(gbase) + (voff)[_i]), (PG8_LAS unsigned*)(lds + (bufoff) + ldsw + _i * 8192), 16, 0, 0); } while (0)
; #define PG8_LDA(dst, b, h) do { _Pragma("unroll") for (int m = 0; m < 4; ++m) _Pragma("unroll") for (int k = 0; k < 2; ++k) dst[m][k] = *(const PG8_LAS bf16x8*)(lds + PG8_SA(b, h) + aoff + m * 2048 + k * 1024); } while (0)
; #define PG8_LDB(dst, b, h) do { _Pragma("unroll") for (int n = 0; n < 2; ++n) _Pragma("unroll") for (int k = 0; k < 2; ++k) dst[n][k] = *(const PG8_LAS bf16x8*)(lds + PG8_SB(b, h) + boff + n * 2048 + k * 1024); } while (0)
; #define PG8_MMA(ai, bj, At, Bt) do { __builtin_amdgcn_s_setprio(1); _Pragma("unroll") for (int m = 0; m < 4; ++m) _Pragma("unroll") for (int n = 0; n < 2; ++n) _Pragma("unroll") for (int k = 0; k < 2; ++k) \
;         acc[ai][bj][m][n] = __builtin_amdgcn_mfma_f32_16x16x32_bf16(Bt[n][k], At[m][k], acc[ai][bj][m][n], 0, 0, 0); __builtin_amdgcn_s_setprio(0); } while (0)
; #define PG8_WAIT_V(n) asm volatile("s_waitcnt vmcnt(" #n ")" ::: "memory")
; #define PG8_WAIT_L(n) asm volatile("s_waitcnt lgkmcnt(" #n ")" ::: "memory")
; #define PG8_BAR __builtin_amdgcn_s_barrier()
; #define PG8_SCHED __builtin_amdgcn_sched_barrier(0)
; template <class Epi, class Sched, bool ALIGN_EPI = false, bool SP2 = false>
; __device__ __forceinline__ void gemm_phase(PG8_LAS unsigned char* lds, const Gemm g, const Sched& S, const Epi& E, const int tid) {
;     ...
;             PG8_LDB(B0, 0, 0); PG8_LDB(B1, 0, 1); PG8_SCHED; PG8_LDA(At, 0, 0); PG8_STAGE(PG8_SA(1, 1), a1 + hstep, voffA);
;             PG8_WAIT_V(8); PG8_WAIT_L(0); PG8_BAR; PG8_MMA(0, 0, At, B0); PG8_MMA(0, 1, At, B1); PG8_BAR; PG8_SCHED;
;             PG8_LDA(At, 0, 1); PG8_STAGE(PG8_SB(0, 0), b2, voffB); PG8_STAGE(PG8_SB(0, 1), b2 + hstep, voffB); PG8_STAGE(PG8_SA(0, 0), a2, voffA);
;             PG8_WAIT_V(8); PG8_WAIT_L(0); PG8_BAR; PG8_MMA(1, 0, At, B0); PG8_MMA(1, 1, At, B1); PG8_BAR; PG8_SCHED;
.Lrot0_211:
	v_add_u32_e32 v154, s78, v160
	v_add_u32_e32 v158, s80, v160
	ds_read_b128 v[142:145], v154
	ds_read_b128 v[146:149], v154 offset:1024
	ds_read_b128 v[150:153], v154 offset:2048
	ds_read_b128 v[154:157], v154 offset:3072
	ds_read_b128 v[164:167], v158
	ds_read_b128 v[168:171], v158 offset:1024
	ds_read_b128 v[172:175], v158 offset:2048
	ds_read_b128 v[176:179], v158 offset:3072
	v_lshl_add_u64 v[158:159], s[54:55], 0, v[140:141]
	s_add_i32 m0, s61, 0xc000
	ds_read_b128 v[186:189], v162
	ds_read_b128 v[190:193], v162 offset:1024
	ds_read_b128 v[194:197], v162 offset:2048
	ds_read_b128 v[198:201], v162 offset:3072
	ds_read_b128 v[202:205], v162 offset:4096
	ds_read_b128 v[206:209], v162 offset:5120
	ds_read_b128 v[210:213], v162 offset:6144
	ds_read_b128 v[214:217], v162 offset:7168
	global_load_lds_dwordx4 v[158:159], off
	v_lshl_add_u64 v[158:159], s[54:55], 0, v[138:139]
	s_add_i32 m0, s61, 0xe000
	s_nop 0
	global_load_lds_dwordx4 v[158:159], off
	s_waitcnt vmcnt(8)
	s_waitcnt lgkmcnt(0)
	s_barrier
	s_setprio 1
	s_waitcnt lgkmcnt(0)
	v_mfma_f32_16x16x32_bf16 v[130:133], v[142:145], v[186:189], v[130:133]
	v_mfma_f32_16x16x32_bf16 v[126:129], v[150:153], v[186:189], v[126:129]
	v_mfma_f32_16x16x32_bf16 v[114:117], v[142:145], v[194:197], v[114:117]
	v_mfma_f32_16x16x32_bf16 v[106:109], v[150:153], v[194:197], v[106:109]
	v_mfma_f32_16x16x32_bf16 v[92:95], v[142:145], v[202:205], v[92:95]
	v_mfma_f32_16x16x32_bf16 v[84:87], v[150:153], v[202:205], v[84:87]
	v_mfma_f32_16x16x32_bf16 v[76:79], v[142:145], v[210:213], v[76:79]
	v_mfma_f32_16x16x32_bf16 v[68:71], v[150:153], v[210:213], v[68:71]
	v_mfma_f32_16x16x32_bf16 v[130:133], v[146:149], v[190:193], v[130:133]
	v_mfma_f32_16x16x32_bf16 v[126:129], v[154:157], v[190:193], v[126:129]
	v_mfma_f32_16x16x32_bf16 v[114:117], v[146:149], v[198:201], v[114:117]
	v_mfma_f32_16x16x32_bf16 v[106:109], v[154:157], v[198:201], v[106:109]
	v_mfma_f32_16x16x32_bf16 v[92:95], v[146:149], v[206:209], v[92:95]
	v_mfma_f32_16x16x32_bf16 v[84:87], v[154:157], v[206:209], v[84:87]
	v_mfma_f32_16x16x32_bf16 v[76:79], v[146:149], v[214:217], v[76:79]
	v_mfma_f32_16x16x32_bf16 v[68:71], v[154:157], v[214:217], v[68:71]
	s_setprio 0
	s_setprio 1
	v_mfma_f32_16x16x32_bf16 v[122:125], v[164:167], v[186:189], v[122:125]
	v_mfma_f32_16x16x32_bf16 v[118:121], v[172:175], v[186:189], v[118:121]
	v_mfma_f32_16x16x32_bf16 v[110:113], v[164:167], v[194:197], v[110:113]
	v_mfma_f32_16x16x32_bf16 v[102:105], v[172:175], v[194:197], v[102:105]
	v_mfma_f32_16x16x32_bf16 v[88:91], v[164:167], v[202:205], v[88:91]
	v_mfma_f32_16x16x32_bf16 v[80:83], v[172:175], v[202:205], v[80:83]
	v_mfma_f32_16x16x32_bf16 v[72:75], v[164:167], v[210:213], v[72:75]
	v_mfma_f32_16x16x32_bf16 v[64:67], v[172:175], v[210:213], v[64:67]
	v_mfma_f32_16x16x32_bf16 v[122:125], v[168:171], v[190:193], v[122:125]
	v_mfma_f32_16x16x32_bf16 v[118:121], v[176:179], v[190:193], v[118:121]
	v_mfma_f32_16x16x32_bf16 v[110:113], v[168:171], v[198:201], v[110:113]
	v_mfma_f32_16x16x32_bf16 v[102:105], v[176:179], v[198:201], v[102:105]
	v_mfma_f32_16x16x32_bf16 v[88:91], v[168:171], v[206:209], v[88:91]
	v_mfma_f32_16x16x32_bf16 v[80:83], v[176:179], v[206:209], v[80:83]
	v_mfma_f32_16x16x32_bf16 v[72:75], v[168:171], v[214:217], v[72:75]
	v_mfma_f32_16x16x32_bf16 v[64:67], v[176:179], v[214:217], v[64:67]
	s_setprio 0
	s_barrier
	s_add_i32 s78, s78, s60
	v_lshl_add_u64 v[158:159], s[56:57], 0, v[96:97]
	s_mov_b32 m0, s78
	ds_read_b128 v[186:189], v162 offset:16384
	ds_read_b128 v[190:193], v162 offset:17408
	ds_read_b128 v[194:197], v162 offset:18432
	ds_read_b128 v[198:201], v162 offset:19456
	ds_read_b128 v[202:205], v162 offset:20480
	ds_read_b128 v[206:209], v162 offset:21504
	ds_read_b128 v[210:213], v162 offset:22528
	ds_read_b128 v[214:217], v162 offset:23552
	global_load_lds_dwordx4 v[158:159], off
	s_add_i32 m0, s78, 0x2000
	s_add_u32 s78, s56, 0x80000
	v_lshl_add_u64 v[180:181], s[56:57], 0, v[98:99]
	s_addc_u32 s79, s57, 0
	s_add_i32 s80, s80, s60
	global_load_lds_dwordx4 v[180:181], off
	v_lshl_add_u64 v[218:219], s[78:79], 0, v[96:97]
	s_mov_b32 m0, s80
	v_lshl_add_u64 v[220:221], s[58:59], 0, v[134:135]
	global_load_lds_dwordx4 v[218:219], off
	v_lshl_add_u64 v[218:219], s[78:79], 0, v[98:99]
	s_add_i32 m0, s80, 0x2000
	s_nop 0
	global_load_lds_dwordx4 v[218:219], off
	v_lshl_add_u64 v[218:219], s[58:59], 0, v[136:137]
	s_mov_b32 m0, s61
	s_nop 0
	global_load_lds_dwordx4 v[218:219], off
	s_mov_b32 m0, s64
	s_nop 0
	global_load_lds_dwordx4 v[220:221], off
	s_waitcnt vmcnt(8)
	s_waitcnt lgkmcnt(0)
	s_barrier
; #define PG8_STAGE(bufoff, gbase, voff) do { _Pragma("unroll") for (int _i = 0; _i < 2; ++_i) \
;         __builtin_amdgcn_global_load_lds((const unsigned*)((const char*)(gbase) + (voff)[_i]), (PG8_LAS unsigned*)(lds + (bufoff) + ldsw + _i * 8192), 16, 0, 0); } while (0)
; #define PG8_LDA(dst, b, h) do { _Pragma("unroll") for (int m = 0; m < 4; ++m) _Pragma("unroll") for (int k = 0; k < 2; ++k) dst[m][k] = *(const PG8_LAS bf16x8*)(lds + PG8_SA(b, h) + aoff + m * 2048 + k * 1024); } while (0)
; #define PG8_LDB(dst, b, h) do { _Pragma("unroll") for (int n = 0; n < 2; ++n) _Pragma("unroll") for (int k = 0; k < 2; ++k) dst[n][k] = *(const PG8_LAS bf16x8*)(lds + PG8_SB(b, h) + boff + n * 2048 + k * 1024); } while (0)
; #define PG8_MMA(ai, bj, At, Bt) do { __builtin_amdgcn_s_setprio(1); _Pragma("unroll") for (int m = 0; m < 4; ++m) _Pragma("unroll") for (int n = 0; n < 2; ++n) _Pragma("unroll") for (int k = 0; k < 2; ++k) \
;         acc[ai][bj][m][n] = __builtin_amdgcn_mfma_f32_16x16x32_bf16(Bt[n][k], At[m][k], acc[ai][bj][m][n], 0, 0, 0); __builtin_amdgcn_s_setprio(0); } while (0)
; #define PG8_WAIT_V(n) asm volatile("s_waitcnt vmcnt(" #n ")" ::: "memory")
; #define PG8_WAIT_L(n) asm volatile("s_waitcnt lgkmcnt(" #n ")" ::: "memory")
; #define PG8_BAR __builtin_amdgcn_s_barrier()
; #define PG8_SCHED __builtin_amdgcn_sched_barrier(0)
; template <class Epi, class Sched, bool ALIGN_EPI = false, bool SP2 = false>
; __device__ __forceinline__ void gemm_phase(PG8_LAS unsigned char* lds, const Gemm g, const Sched& S, const Epi& E, const int tid) {
;     ...
;             PG8_WAIT_V(8); PG8_WAIT_L(0); PG8_BAR; PG8_MMA(1, 0, At, B0); PG8_MMA(1, 1, At, B1); PG8_BAR; PG8_SCHED;
;             PG8_LDB(B0, 1, 0); PG8_LDB(B1, 1, 1); PG8_SCHED; PG8_LDA(At, 1, 0); PG8_STAGE(PG8_SA(0, 1), a2 + hstep, voffA);
;             PG8_WAIT_V(8); PG8_WAIT_L(0); PG8_BAR; PG8_MMA(0, 0, At, B0); PG8_MMA(0, 1, At, B1); PG8_BAR; PG8_SCHED;
	s_setprio 1
	s_waitcnt lgkmcnt(0)
	v_mfma_f32_16x16x32_bf16 v[60:63], v[142:145], v[186:189], v[60:63]
	v_mfma_f32_16x16x32_bf16 v[52:55], v[150:153], v[186:189], v[52:55]
	v_mfma_f32_16x16x32_bf16 v[44:47], v[142:145], v[194:197], v[44:47]
	v_mfma_f32_16x16x32_bf16 v[36:39], v[150:153], v[194:197], v[36:39]
	v_mfma_f32_16x16x32_bf16 v[28:31], v[142:145], v[202:205], v[28:31]
	v_mfma_f32_16x16x32_bf16 v[20:23], v[150:153], v[202:205], v[20:23]
	v_mfma_f32_16x16x32_bf16 v[12:15], v[142:145], v[210:213], v[12:15]
	v_mfma_f32_16x16x32_bf16 v[4:7], v[150:153], v[210:213], v[4:7]
	v_mfma_f32_16x16x32_bf16 v[60:63], v[146:149], v[190:193], v[60:63]
	v_mfma_f32_16x16x32_bf16 v[52:55], v[154:157], v[190:193], v[52:55]
	v_mfma_f32_16x16x32_bf16 v[44:47], v[146:149], v[198:201], v[44:47]
	v_mfma_f32_16x16x32_bf16 v[36:39], v[154:157], v[198:201], v[36:39]
	v_mfma_f32_16x16x32_bf16 v[28:31], v[146:149], v[206:209], v[28:31]
	v_mfma_f32_16x16x32_bf16 v[20:23], v[154:157], v[206:209], v[20:23]
	v_mfma_f32_16x16x32_bf16 v[12:15], v[146:149], v[214:217], v[12:15]
	v_mfma_f32_16x16x32_bf16 v[4:7], v[154:157], v[214:217], v[4:7]
	s_setprio 0
	s_setprio 1
	v_mfma_f32_16x16x32_bf16 v[56:59], v[164:167], v[186:189], v[56:59]
	v_mfma_f32_16x16x32_bf16 v[48:51], v[172:175], v[186:189], v[48:51]
	v_mfma_f32_16x16x32_bf16 v[40:43], v[164:167], v[194:197], v[40:43]
	v_mfma_f32_16x16x32_bf16 v[32:35], v[172:175], v[194:197], v[32:35]
	v_mfma_f32_16x16x32_bf16 v[24:27], v[164:167], v[202:205], v[24:27]
	v_mfma_f32_16x16x32_bf16 v[16:19], v[172:175], v[202:205], v[16:19]
	v_mfma_f32_16x16x32_bf16 v[8:11], v[164:167], v[210:213], v[8:11]
	v_mfma_f32_16x16x32_bf16 v[0:3], v[172:175], v[210:213], v[0:3]
	v_mfma_f32_16x16x32_bf16 v[56:59], v[168:171], v[190:193], v[56:59]
	v_mfma_f32_16x16x32_bf16 v[48:51], v[176:179], v[190:193], v[48:51]
	v_mfma_f32_16x16x32_bf16 v[40:43], v[168:171], v[198:201], v[40:43]
	v_mfma_f32_16x16x32_bf16 v[32:35], v[176:179], v[198:201], v[32:35]
	v_mfma_f32_16x16x32_bf16 v[24:27], v[168:171], v[206:209], v[24:27]
	v_mfma_f32_16x16x32_bf16 v[16:19], v[176:179], v[206:209], v[16:19]
	v_mfma_f32_16x16x32_bf16 v[8:11], v[168:171], v[214:217], v[8:11]
	v_mfma_f32_16x16x32_bf16 v[0:3], v[176:179], v[214:217], v[0:3]
	s_setprio 0
	s_barrier
	s_add_i32 s78, 0, 0x18000
	s_add_i32 s79, 0, 0x1c000
	v_add_u32_e32 v154, s78, v160
	v_add_u32_e32 v163, s79, v160
	ds_read_b128 v[142:145], v154
	ds_read_b128 v[146:149], v154 offset:1024
	ds_read_b128 v[150:153], v154 offset:2048
	ds_read_b128 v[154:157], v154 offset:3072
	ds_read_b128 v[164:167], v163
	ds_read_b128 v[168:171], v163 offset:1024
	ds_read_b128 v[172:175], v163 offset:2048
	ds_read_b128 v[176:179], v163 offset:3072
	s_add_u32 s58, s58, 0x80000
	s_addc_u32 s59, s59, 0
	s_mov_b32 m0, s65
	v_lshl_add_u64 v[222:223], s[58:59], 0, v[136:137]
	ds_read_b128 v[186:189], v162 offset:32768
	ds_read_b128 v[190:193], v162 offset:33792
	ds_read_b128 v[194:197], v162 offset:34816
	ds_read_b128 v[198:201], v162 offset:35840
	ds_read_b128 v[202:205], v162 offset:36864
	ds_read_b128 v[206:209], v162 offset:37888
	ds_read_b128 v[210:213], v162 offset:38912
	ds_read_b128 v[214:217], v162 offset:39936
	global_load_lds_dwordx4 v[222:223], off
	v_lshl_add_u64 v[222:223], s[58:59], 0, v[134:135]
	s_mov_b32 m0, s66
	s_nop 0
	global_load_lds_dwordx4 v[222:223], off
	s_waitcnt vmcnt(8)
	s_waitcnt lgkmcnt(0)
	s_barrier
	s_setprio 1
	s_waitcnt lgkmcnt(0)
	v_mfma_f32_16x16x32_bf16 v[130:133], v[142:145], v[186:189], v[130:133]
	v_mfma_f32_16x16x32_bf16 v[126:129], v[150:153], v[186:189], v[126:129]
	v_mfma_f32_16x16x32_bf16 v[114:117], v[142:145], v[194:197], v[114:117]
	v_mfma_f32_16x16x32_bf16 v[106:109], v[150:153], v[194:197], v[106:109]
	v_mfma_f32_16x16x32_bf16 v[92:95], v[142:145], v[202:205], v[92:95]
	v_mfma_f32_16x16x32_bf16 v[84:87], v[150:153], v[202:205], v[84:87]
	v_mfma_f32_16x16x32_bf16 v[76:79], v[142:145], v[210:213], v[76:79]
	v_mfma_f32_16x16x32_bf16 v[68:71], v[150:153], v[210:213], v[68:71]
	v_mfma_f32_16x16x32_bf16 v[130:133], v[146:149], v[190:193], v[130:133]
	v_mfma_f32_16x16x32_bf16 v[126:129], v[154:157], v[190:193], v[126:129]
	v_mfma_f32_16x16x32_bf16 v[114:117], v[146:149], v[198:201], v[114:117]
	v_mfma_f32_16x16x32_bf16 v[106:109], v[154:157], v[198:201], v[106:109]
	v_mfma_f32_16x16x32_bf16 v[92:95], v[146:149], v[206:209], v[92:95]
	v_mfma_f32_16x16x32_bf16 v[84:87], v[154:157], v[206:209], v[84:87]
	v_mfma_f32_16x16x32_bf16 v[76:79], v[146:149], v[214:217], v[76:79]
	v_mfma_f32_16x16x32_bf16 v[68:71], v[154:157], v[214:217], v[68:71]
	s_setprio 0
	s_setprio 1
	v_mfma_f32_16x16x32_bf16 v[122:125], v[164:167], v[186:189], v[122:125]
	v_mfma_f32_16x16x32_bf16 v[118:121], v[172:175], v[186:189], v[118:121]
	v_mfma_f32_16x16x32_bf16 v[110:113], v[164:167], v[194:197], v[110:113]
	v_mfma_f32_16x16x32_bf16 v[102:105], v[172:175], v[194:197], v[102:105]
	v_mfma_f32_16x16x32_bf16 v[88:91], v[164:167], v[202:205], v[88:91]
	v_mfma_f32_16x16x32_bf16 v[80:83], v[172:175], v[202:205], v[80:83]
	v_mfma_f32_16x16x32_bf16 v[72:75], v[164:167], v[210:213], v[72:75]
	v_mfma_f32_16x16x32_bf16 v[64:67], v[172:175], v[210:213], v[64:67]
	v_mfma_f32_16x16x32_bf16 v[122:125], v[168:171], v[190:193], v[122:125]
	v_mfma_f32_16x16x32_bf16 v[118:121], v[176:179], v[190:193], v[118:121]
	v_mfma_f32_16x16x32_bf16 v[110:113], v[168:171], v[198:201], v[110:113]
	v_mfma_f32_16x16x32_bf16 v[102:105], v[176:179], v[198:201], v[102:105]
	v_mfma_f32_16x16x32_bf16 v[88:91], v[168:171], v[206:209], v[88:91]
	v_mfma_f32_16x16x32_bf16 v[80:83], v[176:179], v[206:209], v[80:83]
	v_mfma_f32_16x16x32_bf16 v[72:75], v[168:171], v[214:217], v[72:75]
	v_mfma_f32_16x16x32_bf16 v[64:67], v[176:179], v[214:217], v[64:67]
	s_setprio 0
	s_barrier
; #define PG8_STAGE(bufoff, gbase, voff) do { _Pragma("unroll") for (int _i = 0; _i < 2; ++_i) \
;         __builtin_amdgcn_global_load_lds((const unsigned*)((const char*)(gbase) + (voff)[_i]), (PG8_LAS unsigned*)(lds + (bufoff) + ldsw + _i * 8192), 16, 0, 0); } while (0)
; #define PG8_LDA(dst, b, h) do { _Pragma("unroll") for (int m = 0; m < 4; ++m) _Pragma("unroll") for (int k = 0; k < 2; ++k) dst[m][k] = *(const PG8_LAS bf16x8*)(lds + PG8_SA(b, h) + aoff + m * 2048 + k * 1024); } while (0)
; #define PG8_MMA(ai, bj, At, Bt) do { __builtin_amdgcn_s_setprio(1); _Pragma("unroll") for (int m = 0; m < 4; ++m) _Pragma("unroll") for (int n = 0; n < 2; ++n) _Pragma("unroll") for (int k = 0; k < 2; ++k) \
;         acc[ai][bj][m][n] = __builtin_amdgcn_mfma_f32_16x16x32_bf16(Bt[n][k], At[m][k], acc[ai][bj][m][n], 0, 0, 0); __builtin_amdgcn_s_setprio(0); } while (0)
; #define PG8_WAIT_V(n) asm volatile("s_waitcnt vmcnt(" #n ")" ::: "memory")
; #define PG8_WAIT_L(n) asm volatile("s_waitcnt lgkmcnt(" #n ")" ::: "memory")
; #define PG8_BAR __builtin_amdgcn_s_barrier()
; #define PG8_SCHED __builtin_amdgcn_sched_barrier(0)
; template <class Epi, class Sched, bool ALIGN_EPI = false, bool SP2 = false>
; __device__ __forceinline__ void gemm_phase(PG8_LAS unsigned char* lds, const Gemm g, const Sched& S, const Epi& E, const int tid) {
;     ...
;         for (int t = 0; t < nt; t += 2) {
;             const bool last = (t == nt - 2);
;             const char* a1 = cA + (size_t)(t + 1) * kstep;
;             const char* a2 = last ? nA : cA + (size_t)(t + 2) * kstep; const char* b2 = last ? nB : cB + (size_t)(t + 2) * kstep;
;             const char* a3 = a2 + kstep; const char* b3 = b2 + kstep;
;     ...
;             PG8_LDA(At, 1, 1); PG8_STAGE(PG8_SB(1, 0), b3, voffB); PG8_STAGE(PG8_SB(1, 1), b3 + hstep, voffB); PG8_STAGE(PG8_SA(1, 0), a3, voffA);
;             PG8_WAIT_V(8); PG8_WAIT_L(0); PG8_BAR; PG8_MMA(1, 0, At, B0); PG8_MMA(1, 1, At, B1); PG8_BAR; PG8_SCHED;
	s_add_i32 s58, s78, s60
	v_lshl_add_u64 v[158:159], v[158:159], 0, s[28:29]
	s_mov_b32 m0, s58
	ds_read_b128 v[186:189], v162 offset:49152
	ds_read_b128 v[190:193], v162 offset:50176
	ds_read_b128 v[194:197], v162 offset:51200
	ds_read_b128 v[198:201], v162 offset:52224
	ds_read_b128 v[202:205], v162 offset:53248
	ds_read_b128 v[206:209], v162 offset:54272
	ds_read_b128 v[210:213], v162 offset:55296
	ds_read_b128 v[214:217], v162 offset:56320
	global_load_lds_dwordx4 v[158:159], off
	s_add_i32 m0, s58, 0x2000
	s_add_u32 s56, s56, 0x80080
	v_lshl_add_u64 v[158:159], v[180:181], 0, s[28:29]
	s_addc_u32 s57, s57, 0
	s_add_i32 s58, s79, s60
	global_load_lds_dwordx4 v[158:159], off
	v_lshl_add_u64 v[158:159], s[56:57], 0, v[96:97]
	s_mov_b32 m0, s58
	s_nop 0
	global_load_lds_dwordx4 v[158:159], off
	v_lshl_add_u64 v[158:159], s[56:57], 0, v[98:99]
	s_add_i32 m0, s58, 0x2000
	s_nop 0
	global_load_lds_dwordx4 v[158:159], off
	v_lshl_add_u64 v[158:159], v[218:219], 0, s[28:29]
	s_mov_b32 m0, s67
	s_nop 0
	global_load_lds_dwordx4 v[158:159], off
	v_lshl_add_u64 v[158:159], v[220:221], 0, s[28:29]
	s_mov_b32 m0, s68
	s_nop 0
	global_load_lds_dwordx4 v[158:159], off
	s_waitcnt vmcnt(8)
	s_waitcnt lgkmcnt(0)
	s_barrier
	s_setprio 1
	s_waitcnt lgkmcnt(0)
	v_mfma_f32_16x16x32_bf16 v[60:63], v[142:145], v[186:189], v[60:63]
	v_mfma_f32_16x16x32_bf16 v[52:55], v[150:153], v[186:189], v[52:55]
	v_mfma_f32_16x16x32_bf16 v[44:47], v[142:145], v[194:197], v[44:47]
	v_mfma_f32_16x16x32_bf16 v[36:39], v[150:153], v[194:197], v[36:39]
	v_mfma_f32_16x16x32_bf16 v[28:31], v[142:145], v[202:205], v[28:31]
	v_mfma_f32_16x16x32_bf16 v[20:23], v[150:153], v[202:205], v[20:23]
	v_mfma_f32_16x16x32_bf16 v[12:15], v[142:145], v[210:213], v[12:15]
	v_mfma_f32_16x16x32_bf16 v[4:7], v[150:153], v[210:213], v[4:7]
	v_mfma_f32_16x16x32_bf16 v[60:63], v[146:149], v[190:193], v[60:63]
	v_mfma_f32_16x16x32_bf16 v[52:55], v[154:157], v[190:193], v[52:55]
	v_mfma_f32_16x16x32_bf16 v[44:47], v[146:149], v[198:201], v[44:47]
	v_mfma_f32_16x16x32_bf16 v[36:39], v[154:157], v[198:201], v[36:39]
	v_mfma_f32_16x16x32_bf16 v[28:31], v[146:149], v[206:209], v[28:31]
	v_mfma_f32_16x16x32_bf16 v[20:23], v[154:157], v[206:209], v[20:23]
	v_mfma_f32_16x16x32_bf16 v[12:15], v[146:149], v[214:217], v[12:15]
	v_mfma_f32_16x16x32_bf16 v[4:7], v[154:157], v[214:217], v[4:7]
	s_setprio 0
	s_setprio 1
	v_mfma_f32_16x16x32_bf16 v[56:59], v[164:167], v[186:189], v[56:59]
	v_mfma_f32_16x16x32_bf16 v[48:51], v[172:175], v[186:189], v[48:51]
	v_mfma_f32_16x16x32_bf16 v[40:43], v[164:167], v[194:197], v[40:43]
	v_mfma_f32_16x16x32_bf16 v[32:35], v[172:175], v[194:197], v[32:35]
	v_mfma_f32_16x16x32_bf16 v[24:27], v[164:167], v[202:205], v[24:27]
	v_mfma_f32_16x16x32_bf16 v[16:19], v[172:175], v[202:205], v[16:19]
	v_mfma_f32_16x16x32_bf16 v[8:11], v[164:167], v[210:213], v[8:11]
	v_mfma_f32_16x16x32_bf16 v[0:3], v[172:175], v[210:213], v[0:3]
	v_mfma_f32_16x16x32_bf16 v[56:59], v[168:171], v[190:193], v[56:59]
	v_mfma_f32_16x16x32_bf16 v[48:51], v[176:179], v[190:193], v[48:51]
	v_mfma_f32_16x16x32_bf16 v[40:43], v[168:171], v[198:201], v[40:43]
	v_mfma_f32_16x16x32_bf16 v[32:35], v[176:179], v[198:201], v[32:35]
	v_mfma_f32_16x16x32_bf16 v[24:27], v[168:171], v[206:209], v[24:27]
	v_mfma_f32_16x16x32_bf16 v[16:19], v[176:179], v[206:209], v[16:19]
	v_mfma_f32_16x16x32_bf16 v[8:11], v[168:171], v[214:217], v[8:11]
	v_mfma_f32_16x16x32_bf16 v[0:3], v[176:179], v[214:217], v[0:3]
	s_setprio 0
	s_add_i32 s77, s77, 2
	s_add_u32 s75, s75, 0x100
	s_addc_u32 s76, s76, 0
	s_add_u32 s54, s54, 0x100
	s_addc_u32 s55, s55, 0
	s_add_u32 s56, s54, 0xfff80080
	s_addc_u32 s57, s55, -1
	s_add_i32 s78, 0, 0x10000
	s_cmp_eq_u32 s77, 28
	s_cselect_b32 s59, s49, s57
	s_cselect_b32 s58, s72, s56
	s_cselect_b32 s57, s47, s76
	s_cselect_b32 s56, s73, s75
	s_add_i32 s80, 0, 0x14000
	s_cmp_gt_u32 s77, 29
	s_barrier
	s_cbranch_scc0 .Lrot0_211
	s_and_b64 vcc, exec, s[44:45]
	s_cbranch_vccz .LBB0_214
	s_barrier

; #define PG8_STAGE(bufoff, gbase, voff) do { _Pragma("unroll") for (int _i = 0; _i < 2; ++_i) \
;         __builtin_amdgcn_global_load_lds((const unsigned*)((const char*)(gbase) + (voff)[_i]), (PG8_LAS unsigned*)(lds + (bufoff) + ldsw + _i * 8192), 16, 0, 0); } while (0)
; #define PG8_LDA(dst, b, h) do { _Pragma("unroll") for (int m = 0; m < 4; ++m) _Pragma("unroll") for (int k = 0; k < 2; ++k) dst[m][k] = *(const PG8_LAS bf16x8*)(lds + PG8_SA(b, h) + aoff + m * 2048 + k * 1024); } while (0)
; #define PG8_LDB(dst, b, h) do { _Pragma("unroll") for (int n = 0; n < 2; ++n) _Pragma("unroll") for (int k = 0; k < 2; ++k) dst[n][k] = *(const PG8_LAS bf16x8*)(lds + PG8_SB(b, h) + boff + n * 2048 + k * 1024); } while (0)
; #define PG8_MMA(ai, bj, At, Bt) do { __builtin_amdgcn_s_setprio(1); _Pragma("unroll") for (int m = 0; m < 4; ++m) _Pragma("unroll") for (int n = 0; n < 2; ++n) _Pragma("unroll") for (int k = 0; k < 2; ++k) \
;         acc[ai][bj][m][n] = __builtin_amdgcn_mfma_f32_16x16x32_bf16(Bt[n][k], At[m][k], acc[ai][bj][m][n], 0, 0, 0); __builtin_amdgcn_s_setprio(0); } while (0)
; #define PG8_WAIT_V(n) asm volatile("s_waitcnt vmcnt(" #n ")" ::: "memory")
; #define PG8_WAIT_L(n) asm volatile("s_waitcnt lgkmcnt(" #n ")" ::: "memory")
; #define PG8_BAR __builtin_amdgcn_s_barrier()
; #define PG8_SCHED __builtin_amdgcn_sched_barrier(0)
; template <class Epi, class Sched, bool ALIGN_EPI = false, bool SP2 = false>
; __device__ __forceinline__ void gemm_phase(PG8_LAS unsigned char* lds, const Gemm g, const Sched& S, const Epi& E, const int tid) {
;     ...
;             PG8_LDB(B0, 0, 0); PG8_LDB(B1, 0, 1); PG8_SCHED; PG8_LDA(At, 0, 0); PG8_STAGE(PG8_SA(1, 1), a1 + hstep, voffA);
;             PG8_WAIT_V(8); PG8_WAIT_L(0); PG8_BAR; PG8_MMA(0, 0, At, B0); PG8_MMA(0, 1, At, B1); PG8_BAR; PG8_SCHED;
;             PG8_LDA(At, 0, 1); PG8_STAGE(PG8_SB(0, 0), b2, voffB); PG8_STAGE(PG8_SB(0, 1), b2 + hstep, voffB); PG8_STAGE(PG8_SA(0, 0), a2, voffA);
;             PG8_WAIT_V(8); PG8_WAIT_L(0); PG8_BAR; PG8_MMA(1, 0, At, B0); PG8_MMA(1, 1, At, B1); PG8_BAR; PG8_SCHED;
.Lrot0_403:
	v_add_u32_e32 v146, s76, v233
	v_add_u32_e32 v162, s77, v233
	ds_read_b128 v[126:129], v146
	ds_read_b128 v[130:133], v146 offset:1024
	ds_read_b128 v[142:145], v146 offset:2048
	ds_read_b128 v[146:149], v146 offset:3072
	ds_read_b128 v[150:153], v162
	ds_read_b128 v[154:157], v162 offset:1024
	ds_read_b128 v[158:161], v162 offset:2048
	ds_read_b128 v[162:165], v162 offset:3072
	v_lshl_add_u64 v[210:211], s[50:51], 0, v[192:193]
	s_add_i32 m0, s60, 0xc000
	ds_read_b128 v[166:169], v236
	ds_read_b128 v[170:173], v236 offset:1024
	ds_read_b128 v[174:177], v236 offset:2048
	ds_read_b128 v[178:181], v236 offset:3072
	ds_read_b128 v[194:197], v236 offset:4096
	ds_read_b128 v[198:201], v236 offset:5120
	ds_read_b128 v[202:205], v236 offset:6144
	ds_read_b128 v[206:209], v236 offset:7168
	global_load_lds_dwordx4 v[210:211], off
	v_lshl_add_u64 v[210:211], s[50:51], 0, v[190:191]
	s_add_i32 m0, s60, 0xe000
	s_nop 0
	global_load_lds_dwordx4 v[210:211], off
	s_waitcnt vmcnt(8)
	s_waitcnt lgkmcnt(0)
	s_barrier
	s_setprio 1
	s_waitcnt lgkmcnt(0)
	v_mfma_f32_16x16x32_bf16 v[138:141], v[126:129], v[166:169], v[138:141]
	v_mfma_f32_16x16x32_bf16 v[134:137], v[142:145], v[166:169], v[134:137]
	v_mfma_f32_16x16x32_bf16 v[114:117], v[126:129], v[174:177], v[114:117]
	v_mfma_f32_16x16x32_bf16 v[110:113], v[142:145], v[174:177], v[110:113]
	v_mfma_f32_16x16x32_bf16 v[92:95], v[126:129], v[194:197], v[92:95]
	v_mfma_f32_16x16x32_bf16 v[88:91], v[142:145], v[194:197], v[88:91]
	v_mfma_f32_16x16x32_bf16 v[76:79], v[126:129], v[202:205], v[76:79]
	v_mfma_f32_16x16x32_bf16 v[72:75], v[142:145], v[202:205], v[72:75]
	v_mfma_f32_16x16x32_bf16 v[138:141], v[130:133], v[170:173], v[138:141]
	v_mfma_f32_16x16x32_bf16 v[134:137], v[146:149], v[170:173], v[134:137]
	v_mfma_f32_16x16x32_bf16 v[114:117], v[130:133], v[178:181], v[114:117]
	v_mfma_f32_16x16x32_bf16 v[110:113], v[146:149], v[178:181], v[110:113]
	v_mfma_f32_16x16x32_bf16 v[92:95], v[130:133], v[198:201], v[92:95]
	v_mfma_f32_16x16x32_bf16 v[88:91], v[146:149], v[198:201], v[88:91]
	v_mfma_f32_16x16x32_bf16 v[76:79], v[130:133], v[206:209], v[76:79]
	v_mfma_f32_16x16x32_bf16 v[72:75], v[146:149], v[206:209], v[72:75]
	s_setprio 0
	s_setprio 1
	v_mfma_f32_16x16x32_bf16 v[122:125], v[150:153], v[166:169], v[122:125]
	v_mfma_f32_16x16x32_bf16 v[118:121], v[158:161], v[166:169], v[118:121]
	v_mfma_f32_16x16x32_bf16 v[106:109], v[150:153], v[174:177], v[106:109]
	v_mfma_f32_16x16x32_bf16 v[102:105], v[158:161], v[174:177], v[102:105]
	v_mfma_f32_16x16x32_bf16 v[84:87], v[150:153], v[194:197], v[84:87]
	v_mfma_f32_16x16x32_bf16 v[80:83], v[158:161], v[194:197], v[80:83]
	v_mfma_f32_16x16x32_bf16 v[68:71], v[150:153], v[202:205], v[68:71]
	v_mfma_f32_16x16x32_bf16 v[64:67], v[158:161], v[202:205], v[64:67]
	v_mfma_f32_16x16x32_bf16 v[122:125], v[154:157], v[170:173], v[122:125]
	v_mfma_f32_16x16x32_bf16 v[118:121], v[162:165], v[170:173], v[118:121]
	v_mfma_f32_16x16x32_bf16 v[106:109], v[154:157], v[178:181], v[106:109]
	v_mfma_f32_16x16x32_bf16 v[102:105], v[162:165], v[178:181], v[102:105]
	v_mfma_f32_16x16x32_bf16 v[84:87], v[154:157], v[198:201], v[84:87]
	v_mfma_f32_16x16x32_bf16 v[80:83], v[162:165], v[198:201], v[80:83]
	v_mfma_f32_16x16x32_bf16 v[68:71], v[154:157], v[206:209], v[68:71]
	v_mfma_f32_16x16x32_bf16 v[64:67], v[162:165], v[206:209], v[64:67]
	s_setprio 0
	s_barrier
	s_add_i32 s50, s76, s59
	v_lshl_add_u64 v[210:211], s[54:55], 0, v[96:97]
	s_mov_b32 m0, s50
	ds_read_b128 v[166:169], v236 offset:16384
	ds_read_b128 v[170:173], v236 offset:17408
	ds_read_b128 v[174:177], v236 offset:18432
	ds_read_b128 v[178:181], v236 offset:19456
	ds_read_b128 v[194:197], v236 offset:20480
	ds_read_b128 v[198:201], v236 offset:21504
	ds_read_b128 v[202:205], v236 offset:22528
	ds_read_b128 v[206:209], v236 offset:23552
	global_load_lds_dwordx4 v[210:211], off
	s_add_i32 m0, s50, 0x2000
	s_add_u32 s50, s54, 0x160000
	v_lshl_add_u64 v[212:213], s[54:55], 0, v[98:99]
	s_addc_u32 s51, s55, 0
	s_add_i32 s76, s77, s59
	global_load_lds_dwordx4 v[212:213], off
	v_lshl_add_u64 v[214:215], s[50:51], 0, v[96:97]
	s_mov_b32 m0, s76
	v_lshl_add_u64 v[216:217], s[56:57], 0, v[186:187]
	global_load_lds_dwordx4 v[214:215], off
	v_lshl_add_u64 v[214:215], s[50:51], 0, v[98:99]
	s_add_i32 m0, s76, 0x2000
	s_nop 0
	global_load_lds_dwordx4 v[214:215], off
	v_lshl_add_u64 v[214:215], s[56:57], 0, v[188:189]
	s_mov_b32 m0, s60
	s_nop 0
	global_load_lds_dwordx4 v[214:215], off
	s_mov_b32 m0, s61
	s_nop 0
	global_load_lds_dwordx4 v[216:217], off
	s_waitcnt vmcnt(8)
	s_waitcnt lgkmcnt(0)
	s_barrier
; #define PG8_STAGE(bufoff, gbase, voff) do { _Pragma("unroll") for (int _i = 0; _i < 2; ++_i) \
;         __builtin_amdgcn_global_load_lds((const unsigned*)((const char*)(gbase) + (voff)[_i]), (PG8_LAS unsigned*)(lds + (bufoff) + ldsw + _i * 8192), 16, 0, 0); } while (0)
; #define PG8_LDA(dst, b, h) do { _Pragma("unroll") for (int m = 0; m < 4; ++m) _Pragma("unroll") for (int k = 0; k < 2; ++k) dst[m][k] = *(const PG8_LAS bf16x8*)(lds + PG8_SA(b, h) + aoff + m * 2048 + k * 1024); } while (0)
; #define PG8_LDB(dst, b, h) do { _Pragma("unroll") for (int n = 0; n < 2; ++n) _Pragma("unroll") for (int k = 0; k < 2; ++k) dst[n][k] = *(const PG8_LAS bf16x8*)(lds + PG8_SB(b, h) + boff + n * 2048 + k * 1024); } while (0)
; #define PG8_MMA(ai, bj, At, Bt) do { __builtin_amdgcn_s_setprio(1); _Pragma("unroll") for (int m = 0; m < 4; ++m) _Pragma("unroll") for (int n = 0; n < 2; ++n) _Pragma("unroll") for (int k = 0; k < 2; ++k) \
;         acc[ai][bj][m][n] = __builtin_amdgcn_mfma_f32_16x16x32_bf16(Bt[n][k], At[m][k], acc[ai][bj][m][n], 0, 0, 0); __builtin_amdgcn_s_setprio(0); } while (0)
; #define PG8_WAIT_V(n) asm volatile("s_waitcnt vmcnt(" #n ")" ::: "memory")
; #define PG8_WAIT_L(n) asm volatile("s_waitcnt lgkmcnt(" #n ")" ::: "memory")
; #define PG8_BAR __builtin_amdgcn_s_barrier()
; #define PG8_SCHED __builtin_amdgcn_sched_barrier(0)
; template <class Epi, class Sched, bool ALIGN_EPI = false, bool SP2 = false>
; __device__ __forceinline__ void gemm_phase(PG8_LAS unsigned char* lds, const Gemm g, const Sched& S, const Epi& E, const int tid) {
;     ...
;             PG8_WAIT_V(8); PG8_WAIT_L(0); PG8_BAR; PG8_MMA(1, 0, At, B0); PG8_MMA(1, 1, At, B1); PG8_BAR; PG8_SCHED;
;             PG8_LDB(B0, 1, 0); PG8_LDB(B1, 1, 1); PG8_SCHED; PG8_LDA(At, 1, 0); PG8_STAGE(PG8_SA(0, 1), a2 + hstep, voffA);
;             PG8_WAIT_V(8); PG8_WAIT_L(0); PG8_BAR; PG8_MMA(0, 0, At, B0); PG8_MMA(0, 1, At, B1); PG8_BAR; PG8_SCHED;
	s_setprio 1
	s_waitcnt lgkmcnt(0)
	v_mfma_f32_16x16x32_bf16 v[60:63], v[126:129], v[166:169], v[60:63]
	v_mfma_f32_16x16x32_bf16 v[56:59], v[142:145], v[166:169], v[56:59]
	v_mfma_f32_16x16x32_bf16 v[44:47], v[126:129], v[174:177], v[44:47]
	v_mfma_f32_16x16x32_bf16 v[40:43], v[142:145], v[174:177], v[40:43]
	v_mfma_f32_16x16x32_bf16 v[28:31], v[126:129], v[194:197], v[28:31]
	v_mfma_f32_16x16x32_bf16 v[24:27], v[142:145], v[194:197], v[24:27]
	v_mfma_f32_16x16x32_bf16 v[12:15], v[126:129], v[202:205], v[12:15]
	v_mfma_f32_16x16x32_bf16 v[8:11], v[142:145], v[202:205], v[8:11]
	v_mfma_f32_16x16x32_bf16 v[60:63], v[130:133], v[170:173], v[60:63]
	v_mfma_f32_16x16x32_bf16 v[56:59], v[146:149], v[170:173], v[56:59]
	v_mfma_f32_16x16x32_bf16 v[44:47], v[130:133], v[178:181], v[44:47]
	v_mfma_f32_16x16x32_bf16 v[40:43], v[146:149], v[178:181], v[40:43]
	v_mfma_f32_16x16x32_bf16 v[28:31], v[130:133], v[198:201], v[28:31]
	v_mfma_f32_16x16x32_bf16 v[24:27], v[146:149], v[198:201], v[24:27]
	v_mfma_f32_16x16x32_bf16 v[12:15], v[130:133], v[206:209], v[12:15]
	v_mfma_f32_16x16x32_bf16 v[8:11], v[146:149], v[206:209], v[8:11]
	s_setprio 0
	s_setprio 1
	v_mfma_f32_16x16x32_bf16 v[52:55], v[150:153], v[166:169], v[52:55]
	v_mfma_f32_16x16x32_bf16 v[48:51], v[158:161], v[166:169], v[48:51]
	v_mfma_f32_16x16x32_bf16 v[36:39], v[150:153], v[174:177], v[36:39]
	v_mfma_f32_16x16x32_bf16 v[32:35], v[158:161], v[174:177], v[32:35]
	v_mfma_f32_16x16x32_bf16 v[20:23], v[150:153], v[194:197], v[20:23]
	v_mfma_f32_16x16x32_bf16 v[16:19], v[158:161], v[194:197], v[16:19]
	v_mfma_f32_16x16x32_bf16 v[4:7], v[150:153], v[202:205], v[4:7]
	v_mfma_f32_16x16x32_bf16 v[0:3], v[158:161], v[202:205], v[0:3]
	v_mfma_f32_16x16x32_bf16 v[52:55], v[154:157], v[170:173], v[52:55]
	v_mfma_f32_16x16x32_bf16 v[48:51], v[162:165], v[170:173], v[48:51]
	v_mfma_f32_16x16x32_bf16 v[36:39], v[154:157], v[178:181], v[36:39]
	v_mfma_f32_16x16x32_bf16 v[32:35], v[162:165], v[178:181], v[32:35]
	v_mfma_f32_16x16x32_bf16 v[20:23], v[154:157], v[198:201], v[20:23]
	v_mfma_f32_16x16x32_bf16 v[16:19], v[162:165], v[198:201], v[16:19]
	v_mfma_f32_16x16x32_bf16 v[4:7], v[154:157], v[206:209], v[4:7]
	v_mfma_f32_16x16x32_bf16 v[0:3], v[162:165], v[206:209], v[0:3]
	s_setprio 0
	s_barrier
	s_add_i32 s76, 0, 0x18000
	s_add_i32 s77, 0, 0x1c000
	v_add_u32_e32 v146, s76, v233
	v_add_u32_e32 v162, s77, v233
	ds_read_b128 v[126:129], v146
	ds_read_b128 v[130:133], v146 offset:1024
	ds_read_b128 v[142:145], v146 offset:2048
	ds_read_b128 v[146:149], v146 offset:3072
	ds_read_b128 v[150:153], v162
	ds_read_b128 v[154:157], v162 offset:1024
	ds_read_b128 v[158:161], v162 offset:2048
	ds_read_b128 v[162:165], v162 offset:3072
	s_add_u32 s50, s56, 0x160000
	s_addc_u32 s51, s57, 0
	s_mov_b32 m0, s64
	v_lshl_add_u64 v[218:219], s[50:51], 0, v[188:189]
	ds_read_b128 v[166:169], v236 offset:32768
	ds_read_b128 v[170:173], v236 offset:33792
	ds_read_b128 v[174:177], v236 offset:34816
	ds_read_b128 v[178:181], v236 offset:35840
	ds_read_b128 v[194:197], v236 offset:36864
	ds_read_b128 v[198:201], v236 offset:37888
	ds_read_b128 v[202:205], v236 offset:38912
	ds_read_b128 v[206:209], v236 offset:39936
	global_load_lds_dwordx4 v[218:219], off
	v_lshl_add_u64 v[218:219], s[50:51], 0, v[186:187]
	s_mov_b32 m0, s65
	s_nop 0
	global_load_lds_dwordx4 v[218:219], off
	s_waitcnt vmcnt(8)
	s_waitcnt lgkmcnt(0)
	s_barrier
	s_setprio 1
	s_waitcnt lgkmcnt(0)
	v_mfma_f32_16x16x32_bf16 v[138:141], v[126:129], v[166:169], v[138:141]
	v_mfma_f32_16x16x32_bf16 v[134:137], v[142:145], v[166:169], v[134:137]
	v_mfma_f32_16x16x32_bf16 v[114:117], v[126:129], v[174:177], v[114:117]
	v_mfma_f32_16x16x32_bf16 v[110:113], v[142:145], v[174:177], v[110:113]
	v_mfma_f32_16x16x32_bf16 v[92:95], v[126:129], v[194:197], v[92:95]
	v_mfma_f32_16x16x32_bf16 v[88:91], v[142:145], v[194:197], v[88:91]
	v_mfma_f32_16x16x32_bf16 v[76:79], v[126:129], v[202:205], v[76:79]
	v_mfma_f32_16x16x32_bf16 v[72:75], v[142:145], v[202:205], v[72:75]
	v_mfma_f32_16x16x32_bf16 v[138:141], v[130:133], v[170:173], v[138:141]
	v_mfma_f32_16x16x32_bf16 v[134:137], v[146:149], v[170:173], v[134:137]
	v_mfma_f32_16x16x32_bf16 v[114:117], v[130:133], v[178:181], v[114:117]
	v_mfma_f32_16x16x32_bf16 v[110:113], v[146:149], v[178:181], v[110:113]
	v_mfma_f32_16x16x32_bf16 v[92:95], v[130:133], v[198:201], v[92:95]
	v_mfma_f32_16x16x32_bf16 v[88:91], v[146:149], v[198:201], v[88:91]
	v_mfma_f32_16x16x32_bf16 v[76:79], v[130:133], v[206:209], v[76:79]
	v_mfma_f32_16x16x32_bf16 v[72:75], v[146:149], v[206:209], v[72:75]
	s_setprio 0
	s_setprio 1
	v_mfma_f32_16x16x32_bf16 v[122:125], v[150:153], v[166:169], v[122:125]
	v_mfma_f32_16x16x32_bf16 v[118:121], v[158:161], v[166:169], v[118:121]
	v_mfma_f32_16x16x32_bf16 v[106:109], v[150:153], v[174:177], v[106:109]
	v_mfma_f32_16x16x32_bf16 v[102:105], v[158:161], v[174:177], v[102:105]
	v_mfma_f32_16x16x32_bf16 v[84:87], v[150:153], v[194:197], v[84:87]
	v_mfma_f32_16x16x32_bf16 v[80:83], v[158:161], v[194:197], v[80:83]
	v_mfma_f32_16x16x32_bf16 v[68:71], v[150:153], v[202:205], v[68:71]
	v_mfma_f32_16x16x32_bf16 v[64:67], v[158:161], v[202:205], v[64:67]
	v_mfma_f32_16x16x32_bf16 v[122:125], v[154:157], v[170:173], v[122:125]
	v_mfma_f32_16x16x32_bf16 v[118:121], v[162:165], v[170:173], v[118:121]
	v_mfma_f32_16x16x32_bf16 v[106:109], v[154:157], v[178:181], v[106:109]
	v_mfma_f32_16x16x32_bf16 v[102:105], v[162:165], v[178:181], v[102:105]
	v_mfma_f32_16x16x32_bf16 v[84:87], v[154:157], v[198:201], v[84:87]
	v_mfma_f32_16x16x32_bf16 v[80:83], v[162:165], v[198:201], v[80:83]
	v_mfma_f32_16x16x32_bf16 v[68:71], v[154:157], v[206:209], v[68:71]
	v_mfma_f32_16x16x32_bf16 v[64:67], v[162:165], v[206:209], v[64:67]
	s_setprio 0
	s_barrier
; #define PG8_GAS __attribute__((address_space(1)))
; #define PG8_STAGE(bufoff, gbase, voff) do { _Pragma("unroll") for (int _i = 0; _i < 2; ++_i) \
;         __builtin_amdgcn_global_load_lds((const unsigned*)((const char*)(gbase) + (voff)[_i]), (PG8_LAS unsigned*)(lds + (bufoff) + ldsw + _i * 8192), 16, 0, 0); } while (0)
; #define PG8_LDA(dst, b, h) do { _Pragma("unroll") for (int m = 0; m < 4; ++m) _Pragma("unroll") for (int k = 0; k < 2; ++k) dst[m][k] = *(const PG8_LAS bf16x8*)(lds + PG8_SA(b, h) + aoff + m * 2048 + k * 1024); } while (0)
; #define PG8_MMA(ai, bj, At, Bt) do { __builtin_amdgcn_s_setprio(1); _Pragma("unroll") for (int m = 0; m < 4; ++m) _Pragma("unroll") for (int n = 0; n < 2; ++n) _Pragma("unroll") for (int k = 0; k < 2; ++k) \
;         acc[ai][bj][m][n] = __builtin_amdgcn_mfma_f32_16x16x32_bf16(Bt[n][k], At[m][k], acc[ai][bj][m][n], 0, 0, 0); __builtin_amdgcn_s_setprio(0); } while (0)
; #define PG8_WAIT_V(n) asm volatile("s_waitcnt vmcnt(" #n ")" ::: "memory")
; #define PG8_WAIT_L(n) asm volatile("s_waitcnt lgkmcnt(" #n ")" ::: "memory")
;     __device__ __forceinline__ void operator()(const f32x4 (&acc)[2][2][4][2], const Unit& u, int wr, int wc, int fr, int fq) const {
;     ...
;                 const int row = row0 + ai * HALF + m * 16; const size_t off = (size_t)row * 2048 + col0, loff = (size_t)row * 2048 + lcol;
;                 L4[m] = *(const PG8_GAS u32x4*)(lin + loff); H4[m][0] = *(const PG8_GAS u32x4*)(hin + off); H4[m][1] = *(const PG8_GAS u32x4*)(hin + off + HALF);
;             }
; template <class Epi, class Sched, bool ALIGN_EPI = false, bool SP2 = false>
; __device__ __forceinline__ void gemm_phase(PG8_LAS unsigned char* lds, const Gemm g, const Sched& S, const Epi& E, const int tid) {
;     ...
;         for (int t = 0; t < nt; t += 2) {
;             const bool last = (t == nt - 2);
;             const char* a1 = cA + (size_t)(t + 1) * kstep;
;             const char* a2 = last ? nA : cA + (size_t)(t + 2) * kstep; const char* b2 = last ? nB : cB + (size_t)(t + 2) * kstep;
;             const char* a3 = a2 + kstep; const char* b3 = b2 + kstep;
;     ...
;             PG8_LDA(At, 1, 1); PG8_STAGE(PG8_SB(1, 0), b3, voffB); PG8_STAGE(PG8_SB(1, 1), b3 + hstep, voffB); PG8_STAGE(PG8_SA(1, 0), a3, voffA);
;             PG8_WAIT_V(8); PG8_WAIT_L(0); PG8_BAR; PG8_MMA(1, 0, At, B0); PG8_MMA(1, 1, At, B1); PG8_BAR; PG8_SCHED;
	s_add_i32 s50, s76, s59
	v_lshl_add_u64 v[210:211], v[210:211], 0, s[28:29]
	s_mov_b32 m0, s50
	ds_read_b128 v[166:169], v236 offset:49152
	ds_read_b128 v[170:173], v236 offset:50176
	ds_read_b128 v[174:177], v236 offset:51200
	ds_read_b128 v[178:181], v236 offset:52224
	ds_read_b128 v[194:197], v236 offset:53248
	ds_read_b128 v[198:201], v236 offset:54272
	ds_read_b128 v[202:205], v236 offset:55296
	ds_read_b128 v[206:209], v236 offset:56320
	global_load_lds_dwordx4 v[210:211], off
	s_add_i32 m0, s50, 0x2000
	s_add_u32 s50, s54, 0x160080
	v_lshl_add_u64 v[210:211], v[212:213], 0, s[28:29]
	s_addc_u32 s51, s55, 0
	s_add_i32 s54, s77, s59
	global_load_lds_dwordx4 v[210:211], off
	v_lshl_add_u64 v[210:211], s[50:51], 0, v[96:97]
	s_mov_b32 m0, s54
	s_nop 0
	global_load_lds_dwordx4 v[210:211], off
	v_lshl_add_u64 v[210:211], s[50:51], 0, v[98:99]
	s_add_i32 m0, s54, 0x2000
	s_nop 0
	global_load_lds_dwordx4 v[210:211], off
	v_lshl_add_u64 v[210:211], v[214:215], 0, s[28:29]
	s_mov_b32 m0, s63
	s_nop 0
	global_load_lds_dwordx4 v[210:211], off
	v_lshl_add_u64 v[210:211], v[216:217], 0, s[28:29]
	s_mov_b32 m0, s66
	s_nop 0
	global_load_lds_dwordx4 v[210:211], off
	s_waitcnt vmcnt(8)
	s_waitcnt lgkmcnt(0)
	s_barrier
	s_setprio 1
	s_waitcnt lgkmcnt(0)
	v_mfma_f32_16x16x32_bf16 v[60:63], v[126:129], v[166:169], v[60:63]
	v_mfma_f32_16x16x32_bf16 v[56:59], v[142:145], v[166:169], v[56:59]
	v_mfma_f32_16x16x32_bf16 v[44:47], v[126:129], v[174:177], v[44:47]
	v_mfma_f32_16x16x32_bf16 v[40:43], v[142:145], v[174:177], v[40:43]
	v_mfma_f32_16x16x32_bf16 v[28:31], v[126:129], v[194:197], v[28:31]
	v_mfma_f32_16x16x32_bf16 v[24:27], v[142:145], v[194:197], v[24:27]
	v_mfma_f32_16x16x32_bf16 v[12:15], v[126:129], v[202:205], v[12:15]
	v_mfma_f32_16x16x32_bf16 v[8:11], v[142:145], v[202:205], v[8:11]
	v_mfma_f32_16x16x32_bf16 v[60:63], v[130:133], v[170:173], v[60:63]
	v_mfma_f32_16x16x32_bf16 v[56:59], v[146:149], v[170:173], v[56:59]
	v_mfma_f32_16x16x32_bf16 v[44:47], v[130:133], v[178:181], v[44:47]
	v_mfma_f32_16x16x32_bf16 v[40:43], v[146:149], v[178:181], v[40:43]
	v_mfma_f32_16x16x32_bf16 v[28:31], v[130:133], v[198:201], v[28:31]
	v_mfma_f32_16x16x32_bf16 v[24:27], v[146:149], v[198:201], v[24:27]
	v_mfma_f32_16x16x32_bf16 v[12:15], v[130:133], v[206:209], v[12:15]
	v_mfma_f32_16x16x32_bf16 v[8:11], v[146:149], v[206:209], v[8:11]
	s_setprio 0
	s_setprio 1
	v_mfma_f32_16x16x32_bf16 v[52:55], v[150:153], v[166:169], v[52:55]
	v_mfma_f32_16x16x32_bf16 v[48:51], v[158:161], v[166:169], v[48:51]
	v_mfma_f32_16x16x32_bf16 v[36:39], v[150:153], v[174:177], v[36:39]
	v_mfma_f32_16x16x32_bf16 v[32:35], v[158:161], v[174:177], v[32:35]
	v_mfma_f32_16x16x32_bf16 v[20:23], v[150:153], v[194:197], v[20:23]
	v_mfma_f32_16x16x32_bf16 v[16:19], v[158:161], v[194:197], v[16:19]
	v_mfma_f32_16x16x32_bf16 v[4:7], v[150:153], v[202:205], v[4:7]
	v_mfma_f32_16x16x32_bf16 v[0:3], v[158:161], v[202:205], v[0:3]
	v_mfma_f32_16x16x32_bf16 v[52:55], v[154:157], v[170:173], v[52:55]
	v_mfma_f32_16x16x32_bf16 v[48:51], v[162:165], v[170:173], v[48:51]
	v_mfma_f32_16x16x32_bf16 v[36:39], v[154:157], v[178:181], v[36:39]
	v_mfma_f32_16x16x32_bf16 v[32:35], v[162:165], v[178:181], v[32:35]
	v_mfma_f32_16x16x32_bf16 v[20:23], v[154:157], v[198:201], v[20:23]
	v_mfma_f32_16x16x32_bf16 v[16:19], v[162:165], v[198:201], v[16:19]
	v_mfma_f32_16x16x32_bf16 v[4:7], v[154:157], v[206:209], v[4:7]
	v_mfma_f32_16x16x32_bf16 v[0:3], v[162:165], v[206:209], v[0:3]
	s_setprio 0
	s_add_i32 s75, s75, 2
	s_add_u32 s72, s72, 0x100
	s_addc_u32 s73, s73, 0
	s_mov_b64 s[50:51], s[52:53]
	s_add_u32 s52, s50, 0x100
	s_addc_u32 s53, s51, 0
	s_add_i32 s76, 0, 0x10000
	s_cmpk_eq_i32 s75, 0x54
	s_cselect_b32 s57, s45, s53
	s_cselect_b32 s56, s44, s52
	s_cselect_b32 s55, s47, s73
	s_cselect_b32 s54, s46, s72
	s_add_i32 s77, 0, 0x14000
	s_cmpk_gt_u32 s75, 0x55
	s_barrier
	s_cbranch_scc0 .Lrot0_403
	v_and_b32_e32 v127, 64, v228
	v_xor_b32_e32 v126, 16, v228
	v_add_u32_e32 v127, 64, v127
	v_cmp_lt_i32_e32 vcc, v126, v127
	s_lshl_b32 s50, s70, 8
	v_lshl_add_u32 v198, s71, 8, v101
	v_cndmask_b32_e32 v126, v228, v126, vcc
	v_or_b32_e32 v194, s50, v235
	v_lshlrev_b32_e32 v238, 2, v126
	v_xor_b32_e32 v126, 32, v228
	v_or_b32_e32 v196, s50, v234
	v_ashrrev_i32_e32 v195, 31, v194
	v_cmp_lt_i32_e32 vcc, v126, v127
	v_ashrrev_i32_e32 v199, 31, v198
	v_ashrrev_i32_e32 v197, 31, v196
	v_cndmask_b32_e32 v126, v228, v126, vcc
	v_lshl_add_u64 v[202:203], s[34:35], 0, v[194:195]
	v_lshlrev_b64 v[216:217], 11, v[198:199]
	v_lshlrev_b32_e32 v237, 2, v126
	v_lshlrev_b64 v[218:219], 1, v[196:197]
	v_lshl_add_u64 v[126:127], v[202:203], 0, v[216:217]
	v_lshl_add_u64 v[200:201], s[30:31], 0, v[218:219]
	global_load_dwordx4 v[170:173], v[126:127], off
	v_lshlrev_b64 v[220:221], 12, v[198:199]
	v_lshl_add_u64 v[126:127], v[200:201], 0, v[220:221]
	global_load_dwordx4 v[178:181], v[126:127], off
	global_load_dwordx4 v[174:177], v[126:127], off offset:256
	v_or_b32_e32 v212, 16, v198
	v_ashrrev_i32_e32 v213, 31, v212
	v_lshlrev_b64 v[214:215], 11, v[212:213]
	v_lshl_add_u64 v[126:127], v[202:203], 0, v[214:215]
	v_or_b32_e32 v208, 32, v198
	global_load_dwordx4 v[158:161], v[126:127], off
	v_lshlrev_b64 v[126:127], 12, v[212:213]
	v_ashrrev_i32_e32 v209, 31, v208
	v_lshl_add_u64 v[126:127], v[200:201], 0, v[126:127]
	v_lshlrev_b64 v[210:211], 11, v[208:209]
	global_load_dwordx4 v[166:169], v[126:127], off
	global_load_dwordx4 v[162:165], v[126:127], off offset:256
	v_lshl_add_u64 v[126:127], v[202:203], 0, v[210:211]
	v_or_b32_e32 v204, 48, v198
	global_load_dwordx4 v[146:149], v[126:127], off
	v_lshlrev_b64 v[126:127], 12, v[208:209]
	v_ashrrev_i32_e32 v205, 31, v204
	v_lshl_add_u64 v[126:127], v[200:201], 0, v[126:127]
	v_lshlrev_b64 v[206:207], 11, v[204:205]
	v_lshlrev_b64 v[130:131], 12, v[204:205]
	global_load_dwordx4 v[154:157], v[126:127], off
	global_load_dwordx4 v[150:153], v[126:127], off offset:256
	v_lshl_add_u64 v[126:127], v[202:203], 0, v[206:207]
	v_lshl_add_u64 v[130:131], v[200:201], 0, v[130:131]
	global_load_dwordx4 v[126:129], v[126:127], off
	s_nop 0
	global_load_dwordx4 v[142:145], v[130:131], off
	s_nop 0
	global_load_dwordx4 v[130:133], v[130:131], off offset:256
	v_mov_b32_e32 v243, v136
	v_mov_b32_e32 v242, v140
	s_waitcnt vmcnt(0)
; #define PG8_GAS __attribute__((address_space(1)))
; __device__ __forceinline__ float e_x24(unsigned h16, unsigned l8) { return __uint_as_float(((h16 - (l8 >> 7)) << 16) | (l8 << 8)); }
;     __device__ __forceinline__ void operator()(const f32x4 (&acc)[2][2][4][2], const Unit& u, int wr, int wc, int fr, int fq) const {
;     ...
;             for (int m = 0; m < 4; ++m) {
;                 const int row = row0 + ai * HALF + m * 16; const size_t off = (size_t)row * 2048 + col0, loff = (size_t)row * 2048 + lcol; float ss = 0.f;
;                 const u32x4 l4 = L4[m];
;                 u32x4 lo4;
; #pragma unroll
;                 for (int bj = 0; bj < 2; ++bj) {
;                     const u32x4 h4 = H4[m][bj];
;                     u32x4 ho;
; #pragma unroll
;                     for (int j = 0; j < 4; ++j) {
;                         const unsigned lw = l4[2 * bj + (j >> 1)], lb0 = (lw >> (16 * (j & 1))) & 0xffu, lb1 = (lw >> (16 * (j & 1) + 8)) & 0xffu;
;                         const float x0 = e_x24(h4[j] & 0xffffu, lb0) + acc[ai][bj][m][j >> 1][2 * (j & 1)] * scale, x1 = e_x24(h4[j] >> 16, lb1) + acc[ai][bj][m][j >> 1][2 * (j & 1) + 1] * scale;
;                         const unsigned b0 = __float_as_uint(x0), b1 = __float_as_uint(x1);
;                         ho[j] = ((b0 + 0x8000u) >> 16) | ((b1 + 0x8000u) & 0xffff0000u);
;                         const unsigned nb = ((b0 >> 8) & 0xffu) | (b1 & 0xff00u);
;                         if ((j & 1) == 0) lo4[2 * bj + (j >> 1)] = nb; else lo4[2 * bj + (j >> 1)] |= nb << 16;
;                         ss += x0 * x0 + x1 * x1;
;                     }
;                     *(PG8_GAS u32x4*)(hout + off + bj * HALF) = ho;
	v_lshrrev_b32_sdwa v222, v229, v171 dst_sel:DWORD dst_unused:UNUSED_PAD src0_sel:DWORD src1_sel:BYTE_0
	v_lshrrev_b32_sdwa v223, v229, v170 dst_sel:DWORD dst_unused:UNUSED_PAD src0_sel:DWORD src1_sel:BYTE_0
	v_sub_u32_sdwa v224, v178, v223 dst_sel:WORD_1 dst_unused:UNUSED_PAD src0_sel:DWORD src1_sel:DWORD
	v_sub_u32_sdwa v222, v180, v222 dst_sel:WORD_1 dst_unused:UNUSED_PAD src0_sel:DWORD src1_sel:DWORD
	v_lshlrev_b32_sdwa v223, v230, v171 dst_sel:DWORD dst_unused:UNUSED_PAD src0_sel:DWORD src1_sel:BYTE_0
	v_lshlrev_b32_sdwa v225, v230, v170 dst_sel:DWORD dst_unused:UNUSED_PAD src0_sel:DWORD src1_sel:BYTE_0
	v_or_b32_e32 v223, v222, v223
	v_or_b32_e32 v222, v224, v225
	v_mov_b32_e32 v224, v138
	v_mov_b32_e32 v225, v134
	v_pk_fma_f32 v[222:223], v[224:225], 0.5, v[222:223] op_sel_hi:[1,0,1]
	v_lshlrev_b32_e32 v224, 1, v170
	v_add_u32_e32 v134, 0x8000, v222
	v_lshrrev_b32_e32 v138, 16, v134
	v_lshlrev_b32_e32 v134, 1, v171
	v_and_b32_e32 v134, 0x10000, v134
	v_and_b32_e32 v224, 0x10000, v224
	v_sub_u32_e32 v134, v180, v134
	v_sub_u32_e32 v178, v178, v224
	v_and_b32_e32 v134, 0xffff0000, v134
	v_and_b32_e32 v178, 0xffff0000, v178
	v_and_b32_e32 v180, 0xff00, v171
	v_and_b32_e32 v224, 0xff00, v170
	v_or_b32_e32 v225, v134, v180
	v_or_b32_e32 v224, v178, v224
	v_mov_b32_e32 v134, v139
	v_pk_fma_f32 v[224:225], v[134:135], 0.5, v[224:225] op_sel_hi:[1,0,1]
	v_and_b32_sdwa v135, v171, s93 dst_sel:DWORD dst_unused:UNUSED_PAD src0_sel:WORD_1 src1_sel:DWORD
	v_and_b32_sdwa v178, v170, s93 dst_sel:DWORD dst_unused:UNUSED_PAD src0_sel:WORD_1 src1_sel:DWORD
	v_lshlrev_b32_sdwa v239, v231, v170 dst_sel:DWORD dst_unused:UNUSED_PAD src0_sel:DWORD src1_sel:BYTE_3
	v_lshlrev_b32_sdwa v136, v231, v171 dst_sel:DWORD dst_unused:UNUSED_PAD src0_sel:DWORD src1_sel:BYTE_3
	v_lshrrev_b32_e32 v180, 7, v178
	v_lshrrev_b32_e32 v240, 7, v135
	v_and_b32_e32 v136, 0x10000, v136
	v_and_b32_e32 v140, 0x10000, v239
	v_sub_u32_sdwa v180, v179, v180 dst_sel:WORD_1 dst_unused:UNUSED_PAD src0_sel:DWORD src1_sel:DWORD
	v_sub_u32_sdwa v240, v181, v240 dst_sel:WORD_1 dst_unused:UNUSED_PAD src0_sel:DWORD src1_sel:DWORD
	v_lshlrev_b32_e32 v135, 8, v135
	v_lshlrev_b32_e32 v178, 8, v178
	v_sub_u32_e32 v136, v181, v136
	v_sub_u32_e32 v140, v179, v140
	v_or_b32_e32 v241, v240, v135
	v_or_b32_e32 v240, v180, v178
	v_and_b32_e32 v136, 0xffff0000, v136
	v_and_b32_e32 v140, 0xffff0000, v140
	v_lshlrev_b32_sdwa v171, v230, v171 dst_sel:DWORD dst_unused:UNUSED_PAD src0_sel:DWORD src1_sel:BYTE_3
	v_lshlrev_b32_sdwa v170, v230, v170 dst_sel:DWORD dst_unused:UNUSED_PAD src0_sel:DWORD src1_sel:BYTE_3
	v_pk_fma_f32 v[240:241], v[242:243], 0.5, v[240:241] op_sel_hi:[1,0,1]
	v_or_b32_e32 v171, v136, v171
	v_or_b32_e32 v170, v140, v170
	v_mov_b32_e32 v136, v141
	v_add_u32_e32 v135, 0x8000, v240
	v_pk_fma_f32 v[140:141], v[136:137], 0.5, v[170:171] op_sel_hi:[1,0,1]
	v_lshrrev_b32_e32 v135, 16, v135
	v_add_u32_e32 v136, 0x8000, v140
	v_and_or_b32 v135, v136, s90, v135
	v_pk_mul_f32 v[136:137], v[140:141], v[140:141]
	v_add_u32_e32 v178, 0x8000, v141
	v_pk_fma_f32 v[170:171], v[240:241], v[240:241], v[136:137]
	v_add_u32_e32 v136, 0x8000, v223
	v_lshrrev_b32_e32 v136, 16, v136
	v_add_u32_e32 v137, 0x8000, v225
	v_and_or_b32 v136, v137, s90, v136
	v_add_u32_e32 v137, 0x8000, v241
	v_lshrrev_b32_e32 v137, 16, v137
	v_add_u32_e32 v134, 0x8000, v224
	v_and_or_b32 v137, v178, s90, v137
	v_lshl_add_u64 v[178:179], s[30:31], 0, v[220:221]
	v_and_or_b32 v134, v134, s90, v138
	v_lshl_add_u64 v[178:179], v[178:179], 0, v[218:219]
	global_store_dwordx4 v[178:179], v[134:137], off
	v_lshlrev_b32_sdwa v220, v231, v172 dst_sel:DWORD dst_unused:UNUSED_PAD src0_sel:DWORD src1_sel:BYTE_3
	v_mov_b32_e32 v219, v120
	v_lshrrev_b32_sdwa v134, v229, v173 dst_sel:DWORD dst_unused:UNUSED_PAD src0_sel:DWORD src1_sel:BYTE_0
	v_lshrrev_b32_sdwa v135, v229, v172 dst_sel:DWORD dst_unused:UNUSED_PAD src0_sel:DWORD src1_sel:BYTE_0
	v_sub_u32_sdwa v136, v174, v135 dst_sel:WORD_1 dst_unused:UNUSED_PAD src0_sel:DWORD src1_sel:DWORD
	v_sub_u32_sdwa v134, v176, v134 dst_sel:WORD_1 dst_unused:UNUSED_PAD src0_sel:DWORD src1_sel:DWORD
	v_lshlrev_b32_sdwa v135, v230, v173 dst_sel:DWORD dst_unused:UNUSED_PAD src0_sel:DWORD src1_sel:BYTE_0
	v_lshlrev_b32_sdwa v137, v230, v172 dst_sel:DWORD dst_unused:UNUSED_PAD src0_sel:DWORD src1_sel:BYTE_0
	v_or_b32_e32 v135, v134, v135
	v_or_b32_e32 v134, v136, v137
	v_mov_b32_e32 v136, v122
	v_mov_b32_e32 v137, v118
	v_pk_fma_f32 v[134:135], v[136:137], 0.5, v[134:135] op_sel_hi:[1,0,1]
; #define PG8_GAS __attribute__((address_space(1)))
; __device__ __forceinline__ float e_x24(unsigned h16, unsigned l8) { return __uint_as_float(((h16 - (l8 >> 7)) << 16) | (l8 << 8)); }
;     __device__ __forceinline__ void operator()(const f32x4 (&acc)[2][2][4][2], const Unit& u, int wr, int wc, int fr, int fq) const {
;     ...
;                 for (int bj = 0; bj < 2; ++bj) {
;                     const u32x4 h4 = H4[m][bj];
;                     u32x4 ho;
; #pragma unroll
;                     for (int j = 0; j < 4; ++j) {
;                         const unsigned lw = l4[2 * bj + (j >> 1)], lb0 = (lw >> (16 * (j & 1))) & 0xffu, lb1 = (lw >> (16 * (j & 1) + 8)) & 0xffu;
;                         const float x0 = e_x24(h4[j] & 0xffffu, lb0) + acc[ai][bj][m][j >> 1][2 * (j & 1)] * scale, x1 = e_x24(h4[j] >> 16, lb1) + acc[ai][bj][m][j >> 1][2 * (j & 1) + 1] * scale;
;                         const unsigned b0 = __float_as_uint(x0), b1 = __float_as_uint(x1);
;                         ho[j] = ((b0 + 0x8000u) >> 16) | ((b1 + 0x8000u) & 0xffff0000u);
;                         const unsigned nb = ((b0 >> 8) & 0xffu) | (b1 & 0xff00u);
;                         if ((j & 1) == 0) lo4[2 * bj + (j >> 1)] = nb; else lo4[2 * bj + (j >> 1)] |= nb << 16;
;                         ss += x0 * x0 + x1 * x1;
;                     }
;                     *(PG8_GAS u32x4*)(hout + off + bj * HALF) = ho;
;                 }
;                 *(PG8_GAS u32x4*)(lout + loff) = lo4;
;                 ss += __shfl_xor(ss, 16); ss += __shfl_xor(ss, 32);
;                 if (fq == 0) __hip_atomic_fetch_add((PG8_GAS unsigned long long*)(rowsq_out + row), (unsigned long long)(ss * 16777216.0f + 0.5f), __ATOMIC_RELAXED, __HIP_MEMORY_SCOPE_AGENT);
	v_lshlrev_b32_e32 v122, 1, v172
	v_add_u32_e32 v118, 0x8000, v134
	v_lshrrev_b32_e32 v180, 16, v118
	v_lshlrev_b32_e32 v118, 1, v173
	v_and_b32_e32 v118, 0x10000, v118
	v_and_b32_e32 v122, 0x10000, v122
	v_sub_u32_e32 v118, v176, v118
	v_sub_u32_e32 v122, v174, v122
	v_and_b32_e32 v118, 0xffff0000, v118
	v_and_b32_e32 v122, 0xffff0000, v122
	v_and_b32_e32 v136, 0xff00, v173
	v_and_b32_e32 v174, 0xff00, v172
	v_or_b32_e32 v137, v118, v136
	v_or_b32_e32 v136, v122, v174
	v_mov_b32_e32 v118, v123
	v_pk_fma_f32 v[122:123], v[118:119], 0.5, v[136:137] op_sel_hi:[1,0,1]
	v_and_b32_sdwa v119, v173, s93 dst_sel:DWORD dst_unused:UNUSED_PAD src0_sel:WORD_1 src1_sel:DWORD
	v_add_u32_e32 v118, 0x8000, v122
	v_and_b32_sdwa v174, v172, s93 dst_sel:DWORD dst_unused:UNUSED_PAD src0_sel:WORD_1 src1_sel:DWORD
	v_lshlrev_b32_sdwa v120, v231, v173 dst_sel:DWORD dst_unused:UNUSED_PAD src0_sel:DWORD src1_sel:BYTE_3
	v_and_or_b32 v118, v118, s90, v180
	v_lshrrev_b32_e32 v176, 7, v174
	v_lshrrev_b32_e32 v180, 7, v119
	v_mov_b32_e32 v218, v124
	v_and_b32_e32 v120, 0x10000, v120
	v_and_b32_e32 v124, 0x10000, v220
	v_sub_u32_sdwa v176, v175, v176 dst_sel:WORD_1 dst_unused:UNUSED_PAD src0_sel:DWORD src1_sel:DWORD
	v_sub_u32_sdwa v180, v177, v180 dst_sel:WORD_1 dst_unused:UNUSED_PAD src0_sel:DWORD src1_sel:DWORD
	v_lshlrev_b32_e32 v119, 8, v119
	v_lshlrev_b32_e32 v174, 8, v174
	v_sub_u32_e32 v120, v177, v120
	v_sub_u32_e32 v124, v175, v124
	v_or_b32_e32 v181, v180, v119
	v_or_b32_e32 v180, v176, v174
	v_and_b32_e32 v120, 0xffff0000, v120
	v_and_b32_e32 v124, 0xffff0000, v124
	v_lshlrev_b32_sdwa v173, v230, v173 dst_sel:DWORD dst_unused:UNUSED_PAD src0_sel:DWORD src1_sel:BYTE_3
	v_lshlrev_b32_sdwa v172, v230, v172 dst_sel:DWORD dst_unused:UNUSED_PAD src0_sel:DWORD src1_sel:BYTE_3
	v_pk_fma_f32 v[180:181], v[218:219], 0.5, v[180:181] op_sel_hi:[1,0,1]
	v_or_b32_e32 v173, v120, v173
	v_or_b32_e32 v172, v124, v172
	v_mov_b32_e32 v120, v125
	v_add_u32_e32 v119, 0x8000, v180
	v_pk_fma_f32 v[124:125], v[120:121], 0.5, v[172:173] op_sel_hi:[1,0,1]
	v_lshrrev_b32_e32 v119, 16, v119
	v_add_u32_e32 v120, 0x8000, v124
	v_pk_mul_f32 v[138:139], v[224:225], v[224:225]
	v_pk_mul_f32 v[136:137], v[122:123], v[122:123]
	v_and_or_b32 v119, v120, s90, v119
	v_pk_mul_f32 v[120:121], v[124:125], v[124:125]
	v_pk_fma_f32 v[138:139], v[222:223], v[222:223], v[138:139]
	v_pk_fma_f32 v[136:137], v[134:135], v[134:135], v[136:137]
	v_pk_fma_f32 v[172:173], v[180:181], v[180:181], v[120:121]
	v_add_u32_e32 v120, 0x8000, v135
	v_lshrrev_b32_e32 v134, 8, v134
	v_lshrrev_b32_e32 v120, 16, v120
	v_add_u32_e32 v121, 0x8000, v123
	v_perm_b32 v122, v122, v134, s94
	v_add_f32_e32 v134, v138, v170
	v_and_or_b32 v120, v121, s90, v120
	v_add_u32_e32 v121, 0x8000, v181
	v_add_f32_e32 v134, v139, v134
	v_lshrrev_b32_e32 v121, 16, v121
	v_add_u32_e32 v174, 0x8000, v125
	v_add_f32_e32 v134, v171, v134
	v_and_or_b32 v121, v174, s90, v121
	v_lshrrev_b32_e32 v174, 8, v181
	v_lshrrev_b32_e32 v175, 8, v180
	v_add_f32_e32 v134, v136, v134
	v_lshrrev_b32_e32 v176, 8, v241
	v_lshrrev_b32_e32 v177, 8, v240
	v_perm_b32 v124, v124, v175, s94
	v_perm_b32 v125, v125, v174, s94
	v_lshrrev_b32_e32 v135, 8, v135
	v_lshrrev_b32_e32 v174, 8, v223
	v_lshrrev_b32_e32 v175, 8, v222
	v_add_f32_e32 v134, v172, v134
	v_perm_b32 v140, v140, v177, s94
	v_perm_b32 v141, v141, v176, s94
	v_perm_b32 v175, v224, v175, s94
	v_perm_b32 v174, v225, v174, s94
	v_perm_b32 v123, v123, v135, s94
	v_add_f32_e32 v134, v137, v134
	global_store_dwordx4 v[178:179], v[118:121], off offset:256
	v_lshl_or_b32 v125, v125, 16, v123
	v_lshl_or_b32 v124, v124, 16, v122
	v_lshl_add_u64 v[118:119], s[34:35], 0, v[216:217]
	v_lshl_or_b32 v123, v141, 16, v174
	v_lshl_or_b32 v122, v140, 16, v175
	v_add_f32_e32 v134, v173, v134
	v_lshl_add_u64 v[118:119], v[118:119], 0, v[194:195]
	global_store_dwordx4 v[118:119], v[122:125], off
	ds_bpermute_b32 v118, v238, v134
	s_waitcnt lgkmcnt(0)
	v_add_f32_e32 v118, v134, v118
	ds_bpermute_b32 v119, v237, v118
	s_and_saveexec_b64 s[50:51], s[40:41]
	s_cbranch_execz .LBB0_406
	s_waitcnt lgkmcnt(0)
	v_add_f32_e32 v118, v118, v119
	v_fma_f32 v118, v118, s80, 0.5
	v_trunc_f32_e32 v118, v118
	v_mul_f32_e32 v119, 0x2f800000, v118
	v_floor_f32_e32 v119, v119
	v_fmac_f32_e32 v118, 0xcf800000, v119
	v_cvt_u32_f32_e32 v118, v118
	v_cvt_u32_f32_e32 v119, v119
	v_lshl_add_u64 v[120:121], v[198:199], 3, s[48:49]
	global_atomic_add_x2 v[120:121], v[118:119], off

; #define PG8_STAGE(bufoff, gbase, voff) do { _Pragma("unroll") for (int _i = 0; _i < 2; ++_i) \
;         __builtin_amdgcn_global_load_lds((const unsigned*)((const char*)(gbase) + (voff)[_i]), (PG8_LAS unsigned*)(lds + (bufoff) + ldsw + _i * 8192), 16, 0, 0); } while (0)
; #define PG8_LDA(dst, b, h) do { _Pragma("unroll") for (int m = 0; m < 4; ++m) _Pragma("unroll") for (int k = 0; k < 2; ++k) dst[m][k] = *(const PG8_LAS bf16x8*)(lds + PG8_SA(b, h) + aoff + m * 2048 + k * 1024); } while (0)
; #define PG8_LDB(dst, b, h) do { _Pragma("unroll") for (int n = 0; n < 2; ++n) _Pragma("unroll") for (int k = 0; k < 2; ++k) dst[n][k] = *(const PG8_LAS bf16x8*)(lds + PG8_SB(b, h) + boff + n * 2048 + k * 1024); } while (0)
; #define PG8_MMA(ai, bj, At, Bt) do { __builtin_amdgcn_s_setprio(1); _Pragma("unroll") for (int m = 0; m < 4; ++m) _Pragma("unroll") for (int n = 0; n < 2; ++n) _Pragma("unroll") for (int k = 0; k < 2; ++k) \
;         acc[ai][bj][m][n] = __builtin_amdgcn_mfma_f32_16x16x32_bf16(Bt[n][k], At[m][k], acc[ai][bj][m][n], 0, 0, 0); __builtin_amdgcn_s_setprio(0); } while (0)
; #define PG8_WAIT_V(n) asm volatile("s_waitcnt vmcnt(" #n ")" ::: "memory")
; #define PG8_WAIT_L(n) asm volatile("s_waitcnt lgkmcnt(" #n ")" ::: "memory")
; #define PG8_BAR __builtin_amdgcn_s_barrier()
; #define PG8_SCHED __builtin_amdgcn_sched_barrier(0)
; template <class Epi, class Sched, bool ALIGN_EPI = false, bool SP2 = false>
; __device__ __forceinline__ void gemm_phase(PG8_LAS unsigned char* lds, const Gemm g, const Sched& S, const Epi& E, const int tid) {
;     ...
;             PG8_LDB(B0, 0, 0); PG8_LDB(B1, 0, 1); PG8_SCHED; PG8_LDA(At, 0, 0); PG8_STAGE(PG8_SA(1, 1), a1 + hstep, voffA);
;             PG8_WAIT_V(8); PG8_WAIT_L(0); PG8_BAR; PG8_MMA(0, 0, At, B0); PG8_MMA(0, 1, At, B1); PG8_BAR; PG8_SCHED;
;             PG8_LDA(At, 0, 1); PG8_STAGE(PG8_SB(0, 0), b2, voffB); PG8_STAGE(PG8_SB(0, 1), b2 + hstep, voffB); PG8_STAGE(PG8_SA(0, 0), a2, voffA);
;             PG8_WAIT_V(8); PG8_WAIT_L(0); PG8_BAR; PG8_MMA(1, 0, At, B0); PG8_MMA(1, 1, At, B1); PG8_BAR; PG8_SCHED;
.Lrot0_488:
	v_add_u32_e32 v156, s78, v163
	v_add_u32_e32 v160, s80, v163
	ds_read_b128 v[144:147], v156
	ds_read_b128 v[148:151], v156 offset:1024
	ds_read_b128 v[152:155], v156 offset:2048
	ds_read_b128 v[156:159], v156 offset:3072
	ds_read_b128 v[166:169], v160
	ds_read_b128 v[170:173], v160 offset:1024
	ds_read_b128 v[174:177], v160 offset:2048
	ds_read_b128 v[178:181], v160 offset:3072
	v_lshl_add_u64 v[160:161], s[42:43], 0, v[142:143]
	s_add_i32 m0, s63, 0xc000
	ds_read_b128 v[186:189], v165
	ds_read_b128 v[190:193], v165 offset:1024
	ds_read_b128 v[194:197], v165 offset:2048
	ds_read_b128 v[198:201], v165 offset:3072
	ds_read_b128 v[202:205], v165 offset:4096
	ds_read_b128 v[206:209], v165 offset:5120
	ds_read_b128 v[210:213], v165 offset:6144
	ds_read_b128 v[214:217], v165 offset:7168
	global_load_lds_dwordx4 v[160:161], off
	v_lshl_add_u64 v[160:161], s[42:43], 0, v[140:141]
	s_add_i32 m0, s63, 0xe000
	s_nop 0
	global_load_lds_dwordx4 v[160:161], off
	s_waitcnt vmcnt(8)
	s_waitcnt lgkmcnt(0)
	s_barrier
	s_setprio 1
	s_waitcnt lgkmcnt(0)
	v_mfma_f32_16x16x32_bf16 v[122:125], v[144:147], v[186:189], v[122:125]
	v_mfma_f32_16x16x32_bf16 v[118:121], v[152:155], v[186:189], v[118:121]
	v_mfma_f32_16x16x32_bf16 v[110:113], v[144:147], v[194:197], v[110:113]
	v_mfma_f32_16x16x32_bf16 v[106:109], v[152:155], v[194:197], v[106:109]
	v_mfma_f32_16x16x32_bf16 v[88:91], v[144:147], v[202:205], v[88:91]
	v_mfma_f32_16x16x32_bf16 v[84:87], v[152:155], v[202:205], v[84:87]
	v_mfma_f32_16x16x32_bf16 v[72:75], v[144:147], v[210:213], v[72:75]
	v_mfma_f32_16x16x32_bf16 v[68:71], v[152:155], v[210:213], v[68:71]
	v_mfma_f32_16x16x32_bf16 v[122:125], v[148:151], v[190:193], v[122:125]
	v_mfma_f32_16x16x32_bf16 v[118:121], v[156:159], v[190:193], v[118:121]
	v_mfma_f32_16x16x32_bf16 v[110:113], v[148:151], v[198:201], v[110:113]
	v_mfma_f32_16x16x32_bf16 v[106:109], v[156:159], v[198:201], v[106:109]
	v_mfma_f32_16x16x32_bf16 v[88:91], v[148:151], v[206:209], v[88:91]
	v_mfma_f32_16x16x32_bf16 v[84:87], v[156:159], v[206:209], v[84:87]
	v_mfma_f32_16x16x32_bf16 v[72:75], v[148:151], v[214:217], v[72:75]
	v_mfma_f32_16x16x32_bf16 v[68:71], v[156:159], v[214:217], v[68:71]
	s_setprio 0
	s_setprio 1
	v_mfma_f32_16x16x32_bf16 v[130:133], v[166:169], v[186:189], v[130:133]
	v_mfma_f32_16x16x32_bf16 v[126:129], v[174:177], v[186:189], v[126:129]
	v_mfma_f32_16x16x32_bf16 v[114:117], v[166:169], v[194:197], v[114:117]
	v_mfma_f32_16x16x32_bf16 v[102:105], v[174:177], v[194:197], v[102:105]
	v_mfma_f32_16x16x32_bf16 v[92:95], v[166:169], v[202:205], v[92:95]
	v_mfma_f32_16x16x32_bf16 v[80:83], v[174:177], v[202:205], v[80:83]
	v_mfma_f32_16x16x32_bf16 v[76:79], v[166:169], v[210:213], v[76:79]
	v_mfma_f32_16x16x32_bf16 v[64:67], v[174:177], v[210:213], v[64:67]
	v_mfma_f32_16x16x32_bf16 v[130:133], v[170:173], v[190:193], v[130:133]
	v_mfma_f32_16x16x32_bf16 v[126:129], v[178:181], v[190:193], v[126:129]
	v_mfma_f32_16x16x32_bf16 v[114:117], v[170:173], v[198:201], v[114:117]
	v_mfma_f32_16x16x32_bf16 v[102:105], v[178:181], v[198:201], v[102:105]
	v_mfma_f32_16x16x32_bf16 v[92:95], v[170:173], v[206:209], v[92:95]
	v_mfma_f32_16x16x32_bf16 v[80:83], v[178:181], v[206:209], v[80:83]
	v_mfma_f32_16x16x32_bf16 v[76:79], v[170:173], v[214:217], v[76:79]
	v_mfma_f32_16x16x32_bf16 v[64:67], v[178:181], v[214:217], v[64:67]
	s_setprio 0
	s_barrier
	s_add_i32 s78, s78, s62
	v_lshl_add_u64 v[160:161], s[58:59], 0, v[96:97]
	s_mov_b32 m0, s78
	ds_read_b128 v[186:189], v165 offset:16384
	ds_read_b128 v[190:193], v165 offset:17408
	ds_read_b128 v[194:197], v165 offset:18432
	ds_read_b128 v[198:201], v165 offset:19456
	ds_read_b128 v[202:205], v165 offset:20480
	ds_read_b128 v[206:209], v165 offset:21504
	ds_read_b128 v[210:213], v165 offset:22528
	ds_read_b128 v[214:217], v165 offset:23552
	global_load_lds_dwordx4 v[160:161], off
	s_add_i32 m0, s78, 0x2000
	s_add_u32 s78, s58, 0x80000
	v_lshl_add_u64 v[218:219], s[58:59], 0, v[98:99]
	s_addc_u32 s79, s59, 0
	s_add_i32 s80, s80, s62
	global_load_lds_dwordx4 v[218:219], off
	v_lshl_add_u64 v[220:221], s[78:79], 0, v[96:97]
	s_mov_b32 m0, s80
	v_lshl_add_u64 v[222:223], s[60:61], 0, v[134:135]
	global_load_lds_dwordx4 v[220:221], off
	v_lshl_add_u64 v[220:221], s[78:79], 0, v[98:99]
	s_add_i32 m0, s80, 0x2000
	s_nop 0
	global_load_lds_dwordx4 v[220:221], off
	v_lshl_add_u64 v[220:221], s[60:61], 0, v[136:137]
	s_mov_b32 m0, s63
	s_nop 0
	global_load_lds_dwordx4 v[220:221], off
	s_mov_b32 m0, s64
	s_nop 0
	global_load_lds_dwordx4 v[222:223], off
	s_waitcnt vmcnt(8)
	s_waitcnt lgkmcnt(0)
	s_barrier
; #define PG8_STAGE(bufoff, gbase, voff) do { _Pragma("unroll") for (int _i = 0; _i < 2; ++_i) \
;         __builtin_amdgcn_global_load_lds((const unsigned*)((const char*)(gbase) + (voff)[_i]), (PG8_LAS unsigned*)(lds + (bufoff) + ldsw + _i * 8192), 16, 0, 0); } while (0)
; #define PG8_LDA(dst, b, h) do { _Pragma("unroll") for (int m = 0; m < 4; ++m) _Pragma("unroll") for (int k = 0; k < 2; ++k) dst[m][k] = *(const PG8_LAS bf16x8*)(lds + PG8_SA(b, h) + aoff + m * 2048 + k * 1024); } while (0)
; #define PG8_LDB(dst, b, h) do { _Pragma("unroll") for (int n = 0; n < 2; ++n) _Pragma("unroll") for (int k = 0; k < 2; ++k) dst[n][k] = *(const PG8_LAS bf16x8*)(lds + PG8_SB(b, h) + boff + n * 2048 + k * 1024); } while (0)
; #define PG8_MMA(ai, bj, At, Bt) do { __builtin_amdgcn_s_setprio(1); _Pragma("unroll") for (int m = 0; m < 4; ++m) _Pragma("unroll") for (int n = 0; n < 2; ++n) _Pragma("unroll") for (int k = 0; k < 2; ++k) \
;         acc[ai][bj][m][n] = __builtin_amdgcn_mfma_f32_16x16x32_bf16(Bt[n][k], At[m][k], acc[ai][bj][m][n], 0, 0, 0); __builtin_amdgcn_s_setprio(0); } while (0)
; #define PG8_WAIT_V(n) asm volatile("s_waitcnt vmcnt(" #n ")" ::: "memory")
; #define PG8_WAIT_L(n) asm volatile("s_waitcnt lgkmcnt(" #n ")" ::: "memory")
; #define PG8_BAR __builtin_amdgcn_s_barrier()
; #define PG8_SCHED __builtin_amdgcn_sched_barrier(0)
; template <class Epi, class Sched, bool ALIGN_EPI = false, bool SP2 = false>
; __device__ __forceinline__ void gemm_phase(PG8_LAS unsigned char* lds, const Gemm g, const Sched& S, const Epi& E, const int tid) {
;     ...
;             PG8_WAIT_V(8); PG8_WAIT_L(0); PG8_BAR; PG8_MMA(1, 0, At, B0); PG8_MMA(1, 1, At, B1); PG8_BAR; PG8_SCHED;
;             PG8_LDB(B0, 1, 0); PG8_LDB(B1, 1, 1); PG8_SCHED; PG8_LDA(At, 1, 0); PG8_STAGE(PG8_SA(0, 1), a2 + hstep, voffA);
;             PG8_WAIT_V(8); PG8_WAIT_L(0); PG8_BAR; PG8_MMA(0, 0, At, B0); PG8_MMA(0, 1, At, B1); PG8_BAR; PG8_SCHED;
	s_setprio 1
	s_waitcnt lgkmcnt(0)
	v_mfma_f32_16x16x32_bf16 v[56:59], v[144:147], v[186:189], v[56:59]
	v_mfma_f32_16x16x32_bf16 v[52:55], v[152:155], v[186:189], v[52:55]
	v_mfma_f32_16x16x32_bf16 v[40:43], v[144:147], v[194:197], v[40:43]
	v_mfma_f32_16x16x32_bf16 v[36:39], v[152:155], v[194:197], v[36:39]
	v_mfma_f32_16x16x32_bf16 v[24:27], v[144:147], v[202:205], v[24:27]
	v_mfma_f32_16x16x32_bf16 v[20:23], v[152:155], v[202:205], v[20:23]
	v_mfma_f32_16x16x32_bf16 v[8:11], v[144:147], v[210:213], v[8:11]
	v_mfma_f32_16x16x32_bf16 v[4:7], v[152:155], v[210:213], v[4:7]
	v_mfma_f32_16x16x32_bf16 v[56:59], v[148:151], v[190:193], v[56:59]
	v_mfma_f32_16x16x32_bf16 v[52:55], v[156:159], v[190:193], v[52:55]
	v_mfma_f32_16x16x32_bf16 v[40:43], v[148:151], v[198:201], v[40:43]
	v_mfma_f32_16x16x32_bf16 v[36:39], v[156:159], v[198:201], v[36:39]
	v_mfma_f32_16x16x32_bf16 v[24:27], v[148:151], v[206:209], v[24:27]
	v_mfma_f32_16x16x32_bf16 v[20:23], v[156:159], v[206:209], v[20:23]
	v_mfma_f32_16x16x32_bf16 v[8:11], v[148:151], v[214:217], v[8:11]
	v_mfma_f32_16x16x32_bf16 v[4:7], v[156:159], v[214:217], v[4:7]
	s_setprio 0
	s_setprio 1
	v_mfma_f32_16x16x32_bf16 v[60:63], v[166:169], v[186:189], v[60:63]
	v_mfma_f32_16x16x32_bf16 v[48:51], v[174:177], v[186:189], v[48:51]
	v_mfma_f32_16x16x32_bf16 v[44:47], v[166:169], v[194:197], v[44:47]
	v_mfma_f32_16x16x32_bf16 v[32:35], v[174:177], v[194:197], v[32:35]
	v_mfma_f32_16x16x32_bf16 v[28:31], v[166:169], v[202:205], v[28:31]
	v_mfma_f32_16x16x32_bf16 v[16:19], v[174:177], v[202:205], v[16:19]
	v_mfma_f32_16x16x32_bf16 v[12:15], v[166:169], v[210:213], v[12:15]
	v_mfma_f32_16x16x32_bf16 v[0:3], v[174:177], v[210:213], v[0:3]
	v_mfma_f32_16x16x32_bf16 v[60:63], v[170:173], v[190:193], v[60:63]
	v_mfma_f32_16x16x32_bf16 v[48:51], v[178:181], v[190:193], v[48:51]
	v_mfma_f32_16x16x32_bf16 v[44:47], v[170:173], v[198:201], v[44:47]
	v_mfma_f32_16x16x32_bf16 v[32:35], v[178:181], v[198:201], v[32:35]
	v_mfma_f32_16x16x32_bf16 v[28:31], v[170:173], v[206:209], v[28:31]
	v_mfma_f32_16x16x32_bf16 v[16:19], v[178:181], v[206:209], v[16:19]
	v_mfma_f32_16x16x32_bf16 v[12:15], v[170:173], v[214:217], v[12:15]
	v_mfma_f32_16x16x32_bf16 v[0:3], v[178:181], v[214:217], v[0:3]
	s_setprio 0
	s_barrier
	s_add_i32 s78, 0, 0x18000
	s_add_i32 s79, 0, 0x1c000
	v_add_u32_e32 v156, s78, v163
	v_add_u32_e32 v162, s79, v163
	ds_read_b128 v[144:147], v156
	ds_read_b128 v[148:151], v156 offset:1024
	ds_read_b128 v[152:155], v156 offset:2048
	ds_read_b128 v[156:159], v156 offset:3072
	ds_read_b128 v[166:169], v162
	ds_read_b128 v[170:173], v162 offset:1024
	ds_read_b128 v[174:177], v162 offset:2048
	ds_read_b128 v[178:181], v162 offset:3072
	s_add_u32 s60, s60, 0x80000
	s_addc_u32 s61, s61, 0
	s_mov_b32 m0, s65
	v_lshl_add_u64 v[224:225], s[60:61], 0, v[136:137]
	ds_read_b128 v[186:189], v165 offset:32768
	ds_read_b128 v[190:193], v165 offset:33792
	ds_read_b128 v[194:197], v165 offset:34816
	ds_read_b128 v[198:201], v165 offset:35840
	ds_read_b128 v[202:205], v165 offset:36864
	ds_read_b128 v[206:209], v165 offset:37888
	ds_read_b128 v[210:213], v165 offset:38912
	ds_read_b128 v[214:217], v165 offset:39936
	global_load_lds_dwordx4 v[224:225], off
	v_lshl_add_u64 v[224:225], s[60:61], 0, v[134:135]
	s_mov_b32 m0, s66
	s_nop 0
	global_load_lds_dwordx4 v[224:225], off
	s_waitcnt vmcnt(8)
	s_waitcnt lgkmcnt(0)
	s_barrier
	s_setprio 1
	s_waitcnt lgkmcnt(0)
	v_mfma_f32_16x16x32_bf16 v[122:125], v[144:147], v[186:189], v[122:125]
	v_mfma_f32_16x16x32_bf16 v[118:121], v[152:155], v[186:189], v[118:121]
	v_mfma_f32_16x16x32_bf16 v[110:113], v[144:147], v[194:197], v[110:113]
	v_mfma_f32_16x16x32_bf16 v[106:109], v[152:155], v[194:197], v[106:109]
	v_mfma_f32_16x16x32_bf16 v[88:91], v[144:147], v[202:205], v[88:91]
	v_mfma_f32_16x16x32_bf16 v[84:87], v[152:155], v[202:205], v[84:87]
	v_mfma_f32_16x16x32_bf16 v[72:75], v[144:147], v[210:213], v[72:75]
	v_mfma_f32_16x16x32_bf16 v[68:71], v[152:155], v[210:213], v[68:71]
	v_mfma_f32_16x16x32_bf16 v[122:125], v[148:151], v[190:193], v[122:125]
	v_mfma_f32_16x16x32_bf16 v[118:121], v[156:159], v[190:193], v[118:121]
	v_mfma_f32_16x16x32_bf16 v[110:113], v[148:151], v[198:201], v[110:113]
	v_mfma_f32_16x16x32_bf16 v[106:109], v[156:159], v[198:201], v[106:109]
	v_mfma_f32_16x16x32_bf16 v[88:91], v[148:151], v[206:209], v[88:91]
	v_mfma_f32_16x16x32_bf16 v[84:87], v[156:159], v[206:209], v[84:87]
	v_mfma_f32_16x16x32_bf16 v[72:75], v[148:151], v[214:217], v[72:75]
	v_mfma_f32_16x16x32_bf16 v[68:71], v[156:159], v[214:217], v[68:71]
	s_setprio 0
	s_setprio 1
	v_mfma_f32_16x16x32_bf16 v[130:133], v[166:169], v[186:189], v[130:133]
	v_mfma_f32_16x16x32_bf16 v[126:129], v[174:177], v[186:189], v[126:129]
	v_mfma_f32_16x16x32_bf16 v[114:117], v[166:169], v[194:197], v[114:117]
	v_mfma_f32_16x16x32_bf16 v[102:105], v[174:177], v[194:197], v[102:105]
	v_mfma_f32_16x16x32_bf16 v[92:95], v[166:169], v[202:205], v[92:95]
	v_mfma_f32_16x16x32_bf16 v[80:83], v[174:177], v[202:205], v[80:83]
	v_mfma_f32_16x16x32_bf16 v[76:79], v[166:169], v[210:213], v[76:79]
	v_mfma_f32_16x16x32_bf16 v[64:67], v[174:177], v[210:213], v[64:67]
	v_mfma_f32_16x16x32_bf16 v[130:133], v[170:173], v[190:193], v[130:133]
	v_mfma_f32_16x16x32_bf16 v[126:129], v[178:181], v[190:193], v[126:129]
	v_mfma_f32_16x16x32_bf16 v[114:117], v[170:173], v[198:201], v[114:117]
	v_mfma_f32_16x16x32_bf16 v[102:105], v[178:181], v[198:201], v[102:105]
	v_mfma_f32_16x16x32_bf16 v[92:95], v[170:173], v[206:209], v[92:95]
	v_mfma_f32_16x16x32_bf16 v[80:83], v[178:181], v[206:209], v[80:83]
	v_mfma_f32_16x16x32_bf16 v[76:79], v[170:173], v[214:217], v[76:79]
	v_mfma_f32_16x16x32_bf16 v[64:67], v[178:181], v[214:217], v[64:67]
	s_setprio 0
	s_barrier
; #define PG8_STAGE(bufoff, gbase, voff) do { _Pragma("unroll") for (int _i = 0; _i < 2; ++_i) \
;         __builtin_amdgcn_global_load_lds((const unsigned*)((const char*)(gbase) + (voff)[_i]), (PG8_LAS unsigned*)(lds + (bufoff) + ldsw + _i * 8192), 16, 0, 0); } while (0)
; #define PG8_LDA(dst, b, h) do { _Pragma("unroll") for (int m = 0; m < 4; ++m) _Pragma("unroll") for (int k = 0; k < 2; ++k) dst[m][k] = *(const PG8_LAS bf16x8*)(lds + PG8_SA(b, h) + aoff + m * 2048 + k * 1024); } while (0)
; #define PG8_MMA(ai, bj, At, Bt) do { __builtin_amdgcn_s_setprio(1); _Pragma("unroll") for (int m = 0; m < 4; ++m) _Pragma("unroll") for (int n = 0; n < 2; ++n) _Pragma("unroll") for (int k = 0; k < 2; ++k) \
;         acc[ai][bj][m][n] = __builtin_amdgcn_mfma_f32_16x16x32_bf16(Bt[n][k], At[m][k], acc[ai][bj][m][n], 0, 0, 0); __builtin_amdgcn_s_setprio(0); } while (0)
; #define PG8_WAIT_V(n) asm volatile("s_waitcnt vmcnt(" #n ")" ::: "memory")
; #define PG8_WAIT_L(n) asm volatile("s_waitcnt lgkmcnt(" #n ")" ::: "memory")
; #define PG8_BAR __builtin_amdgcn_s_barrier()
; #define PG8_SCHED __builtin_amdgcn_sched_barrier(0)
; template <class Epi, class Sched, bool ALIGN_EPI = false, bool SP2 = false>
; __device__ __forceinline__ void gemm_phase(PG8_LAS unsigned char* lds, const Gemm g, const Sched& S, const Epi& E, const int tid) {
;     ...
;         for (int t = 0; t < nt; t += 2) {
;             const bool last = (t == nt - 2);
;             const char* a1 = cA + (size_t)(t + 1) * kstep;
;             const char* a2 = last ? nA : cA + (size_t)(t + 2) * kstep; const char* b2 = last ? nB : cB + (size_t)(t + 2) * kstep;
;             const char* a3 = a2 + kstep; const char* b3 = b2 + kstep;
;     ...
;             PG8_LDA(At, 1, 1); PG8_STAGE(PG8_SB(1, 0), b3, voffB); PG8_STAGE(PG8_SB(1, 1), b3 + hstep, voffB); PG8_STAGE(PG8_SA(1, 0), a3, voffA);
;             PG8_WAIT_V(8); PG8_WAIT_L(0); PG8_BAR; PG8_MMA(1, 0, At, B0); PG8_MMA(1, 1, At, B1); PG8_BAR; PG8_SCHED;
	s_add_i32 s60, s78, s62
	v_lshl_add_u64 v[160:161], v[160:161], 0, s[28:29]
	s_mov_b32 m0, s60
	ds_read_b128 v[186:189], v165 offset:49152
	ds_read_b128 v[190:193], v165 offset:50176
	ds_read_b128 v[194:197], v165 offset:51200
	ds_read_b128 v[198:201], v165 offset:52224
	ds_read_b128 v[202:205], v165 offset:53248
	ds_read_b128 v[206:209], v165 offset:54272
	ds_read_b128 v[210:213], v165 offset:55296
	ds_read_b128 v[214:217], v165 offset:56320
	global_load_lds_dwordx4 v[160:161], off
	s_add_i32 m0, s60, 0x2000
	s_add_u32 s58, s58, 0x80080
	v_lshl_add_u64 v[160:161], v[218:219], 0, s[28:29]
	s_addc_u32 s59, s59, 0
	s_add_i32 s60, s79, s62
	global_load_lds_dwordx4 v[160:161], off
	v_lshl_add_u64 v[160:161], s[58:59], 0, v[96:97]
	s_mov_b32 m0, s60
	s_nop 0
	global_load_lds_dwordx4 v[160:161], off
	v_lshl_add_u64 v[160:161], s[58:59], 0, v[98:99]
	s_add_i32 m0, s60, 0x2000
	s_nop 0
	global_load_lds_dwordx4 v[160:161], off
	v_lshl_add_u64 v[160:161], v[220:221], 0, s[28:29]
	s_mov_b32 m0, s67
	s_nop 0
	global_load_lds_dwordx4 v[160:161], off
	v_lshl_add_u64 v[160:161], v[222:223], 0, s[28:29]
	s_mov_b32 m0, s68
	s_nop 0
	global_load_lds_dwordx4 v[160:161], off
	s_waitcnt vmcnt(8)
	s_waitcnt lgkmcnt(0)
	s_barrier
	s_setprio 1
	s_waitcnt lgkmcnt(0)
	v_mfma_f32_16x16x32_bf16 v[56:59], v[144:147], v[186:189], v[56:59]
	v_mfma_f32_16x16x32_bf16 v[52:55], v[152:155], v[186:189], v[52:55]
	v_mfma_f32_16x16x32_bf16 v[40:43], v[144:147], v[194:197], v[40:43]
	v_mfma_f32_16x16x32_bf16 v[36:39], v[152:155], v[194:197], v[36:39]
	v_mfma_f32_16x16x32_bf16 v[24:27], v[144:147], v[202:205], v[24:27]
	v_mfma_f32_16x16x32_bf16 v[20:23], v[152:155], v[202:205], v[20:23]
	v_mfma_f32_16x16x32_bf16 v[8:11], v[144:147], v[210:213], v[8:11]
	v_mfma_f32_16x16x32_bf16 v[4:7], v[152:155], v[210:213], v[4:7]
	v_mfma_f32_16x16x32_bf16 v[56:59], v[148:151], v[190:193], v[56:59]
	v_mfma_f32_16x16x32_bf16 v[52:55], v[156:159], v[190:193], v[52:55]
	v_mfma_f32_16x16x32_bf16 v[40:43], v[148:151], v[198:201], v[40:43]
	v_mfma_f32_16x16x32_bf16 v[36:39], v[156:159], v[198:201], v[36:39]
	v_mfma_f32_16x16x32_bf16 v[24:27], v[148:151], v[206:209], v[24:27]
	v_mfma_f32_16x16x32_bf16 v[20:23], v[156:159], v[206:209], v[20:23]
	v_mfma_f32_16x16x32_bf16 v[8:11], v[148:151], v[214:217], v[8:11]
	v_mfma_f32_16x16x32_bf16 v[4:7], v[156:159], v[214:217], v[4:7]
	s_setprio 0
	s_setprio 1
	v_mfma_f32_16x16x32_bf16 v[60:63], v[166:169], v[186:189], v[60:63]
	v_mfma_f32_16x16x32_bf16 v[48:51], v[174:177], v[186:189], v[48:51]
	v_mfma_f32_16x16x32_bf16 v[44:47], v[166:169], v[194:197], v[44:47]
	v_mfma_f32_16x16x32_bf16 v[32:35], v[174:177], v[194:197], v[32:35]
	v_mfma_f32_16x16x32_bf16 v[28:31], v[166:169], v[202:205], v[28:31]
	v_mfma_f32_16x16x32_bf16 v[16:19], v[174:177], v[202:205], v[16:19]
	v_mfma_f32_16x16x32_bf16 v[12:15], v[166:169], v[210:213], v[12:15]
	v_mfma_f32_16x16x32_bf16 v[0:3], v[174:177], v[210:213], v[0:3]
	v_mfma_f32_16x16x32_bf16 v[60:63], v[170:173], v[190:193], v[60:63]
	v_mfma_f32_16x16x32_bf16 v[48:51], v[178:181], v[190:193], v[48:51]
	v_mfma_f32_16x16x32_bf16 v[44:47], v[170:173], v[198:201], v[44:47]
	v_mfma_f32_16x16x32_bf16 v[32:35], v[178:181], v[198:201], v[32:35]
	v_mfma_f32_16x16x32_bf16 v[28:31], v[170:173], v[206:209], v[28:31]
	v_mfma_f32_16x16x32_bf16 v[16:19], v[178:181], v[206:209], v[16:19]
	v_mfma_f32_16x16x32_bf16 v[12:15], v[170:173], v[214:217], v[12:15]
	v_mfma_f32_16x16x32_bf16 v[0:3], v[178:181], v[214:217], v[0:3]
	s_setprio 0
	s_add_i32 s77, s77, 2
	s_add_u32 s75, s75, 0x100
	s_addc_u32 s76, s76, 0
	s_add_u32 s42, s42, 0x100
	s_addc_u32 s43, s43, 0
	s_add_u32 s58, s42, 0xfff80080
	s_addc_u32 s59, s43, -1
	s_add_i32 s78, 0, 0x10000
	s_cmp_eq_u32 s77, 28
	s_cselect_b32 s61, s53, s59
	s_cselect_b32 s60, s72, s58
	s_cselect_b32 s59, s51, s76
	s_cselect_b32 s58, s73, s75
	s_add_i32 s80, 0, 0x14000
	s_cmp_gt_u32 s77, 29
	s_barrier
	s_cbranch_scc0 .Lrot0_488
	s_and_b64 vcc, exec, s[46:47]
	s_cbranch_vccz .LBB0_491
	s_barrier

; #define PG8_STAGE(bufoff, gbase, voff) do { _Pragma("unroll") for (int _i = 0; _i < 2; ++_i) \
;         __builtin_amdgcn_global_load_lds((const unsigned*)((const char*)(gbase) + (voff)[_i]), (PG8_LAS unsigned*)(lds + (bufoff) + ldsw + _i * 8192), 16, 0, 0); } while (0)
; #define PG8_LDA(dst, b, h) do { _Pragma("unroll") for (int m = 0; m < 4; ++m) _Pragma("unroll") for (int k = 0; k < 2; ++k) dst[m][k] = *(const PG8_LAS bf16x8*)(lds + PG8_SA(b, h) + aoff + m * 2048 + k * 1024); } while (0)
; #define PG8_LDB(dst, b, h) do { _Pragma("unroll") for (int n = 0; n < 2; ++n) _Pragma("unroll") for (int k = 0; k < 2; ++k) dst[n][k] = *(const PG8_LAS bf16x8*)(lds + PG8_SB(b, h) + boff + n * 2048 + k * 1024); } while (0)
; #define PG8_MMA(ai, bj, At, Bt) do { __builtin_amdgcn_s_setprio(1); _Pragma("unroll") for (int m = 0; m < 4; ++m) _Pragma("unroll") for (int n = 0; n < 2; ++n) _Pragma("unroll") for (int k = 0; k < 2; ++k) \
;         acc[ai][bj][m][n] = __builtin_amdgcn_mfma_f32_16x16x32_bf16(Bt[n][k], At[m][k], acc[ai][bj][m][n], 0, 0, 0); __builtin_amdgcn_s_setprio(0); } while (0)
; #define PG8_WAIT_V(n) asm volatile("s_waitcnt vmcnt(" #n ")" ::: "memory")
; #define PG8_WAIT_L(n) asm volatile("s_waitcnt lgkmcnt(" #n ")" ::: "memory")
; #define PG8_BAR __builtin_amdgcn_s_barrier()
; #define PG8_SCHED __builtin_amdgcn_sched_barrier(0)
; template <class Epi, class Sched, bool ALIGN_EPI = false, bool SP2 = false>
; __device__ __forceinline__ void gemm_phase(PG8_LAS unsigned char* lds, const Gemm g, const Sched& S, const Epi& E, const int tid) {
;     ...
;             PG8_LDB(B0, 0, 0); PG8_LDB(B1, 0, 1); PG8_SCHED; PG8_LDA(At, 0, 0); PG8_STAGE(PG8_SA(1, 1), a1 + hstep, voffA);
;             PG8_WAIT_V(8); PG8_WAIT_L(0); PG8_BAR; PG8_MMA(0, 0, At, B0); PG8_MMA(0, 1, At, B1); PG8_BAR; PG8_SCHED;
;             PG8_LDA(At, 0, 1); PG8_STAGE(PG8_SB(0, 0), b2, voffB); PG8_STAGE(PG8_SB(0, 1), b2 + hstep, voffB); PG8_STAGE(PG8_SA(0, 0), a2, voffA);
;             PG8_WAIT_V(8); PG8_WAIT_L(0); PG8_BAR; PG8_MMA(1, 0, At, B0); PG8_MMA(1, 1, At, B1); PG8_BAR; PG8_SCHED;
.Lrot0_1199:
	v_add_u32_e32 v146, s77, v233
	v_add_u32_e32 v162, s80, v233
	ds_read_b128 v[126:129], v146
	ds_read_b128 v[130:133], v146 offset:1024
	ds_read_b128 v[142:145], v146 offset:2048
	ds_read_b128 v[146:149], v146 offset:3072
	ds_read_b128 v[150:153], v162
	ds_read_b128 v[154:157], v162 offset:1024
	ds_read_b128 v[158:161], v162 offset:2048
	ds_read_b128 v[162:165], v162 offset:3072
	v_lshl_add_u64 v[210:211], s[54:55], 0, v[192:193]
	s_add_i32 m0, s62, 0xc000
	ds_read_b128 v[166:169], v236
	ds_read_b128 v[170:173], v236 offset:1024
	ds_read_b128 v[174:177], v236 offset:2048
	ds_read_b128 v[178:181], v236 offset:3072
	ds_read_b128 v[194:197], v236 offset:4096
	ds_read_b128 v[198:201], v236 offset:5120
	ds_read_b128 v[202:205], v236 offset:6144
	ds_read_b128 v[206:209], v236 offset:7168
	global_load_lds_dwordx4 v[210:211], off
	v_lshl_add_u64 v[210:211], s[54:55], 0, v[190:191]
	s_add_i32 m0, s62, 0xe000
	s_nop 0
	global_load_lds_dwordx4 v[210:211], off
	s_waitcnt vmcnt(8)
	s_waitcnt lgkmcnt(0)
	s_barrier
	s_setprio 1
	s_waitcnt lgkmcnt(0)
	v_mfma_f32_16x16x32_bf16 v[138:141], v[126:129], v[166:169], v[138:141]
	v_mfma_f32_16x16x32_bf16 v[134:137], v[142:145], v[166:169], v[134:137]
	v_mfma_f32_16x16x32_bf16 v[114:117], v[126:129], v[174:177], v[114:117]
	v_mfma_f32_16x16x32_bf16 v[110:113], v[142:145], v[174:177], v[110:113]
	v_mfma_f32_16x16x32_bf16 v[92:95], v[126:129], v[194:197], v[92:95]
	v_mfma_f32_16x16x32_bf16 v[88:91], v[142:145], v[194:197], v[88:91]
	v_mfma_f32_16x16x32_bf16 v[76:79], v[126:129], v[202:205], v[76:79]
	v_mfma_f32_16x16x32_bf16 v[72:75], v[142:145], v[202:205], v[72:75]
	v_mfma_f32_16x16x32_bf16 v[138:141], v[130:133], v[170:173], v[138:141]
	v_mfma_f32_16x16x32_bf16 v[134:137], v[146:149], v[170:173], v[134:137]
	v_mfma_f32_16x16x32_bf16 v[114:117], v[130:133], v[178:181], v[114:117]
	v_mfma_f32_16x16x32_bf16 v[110:113], v[146:149], v[178:181], v[110:113]
	v_mfma_f32_16x16x32_bf16 v[92:95], v[130:133], v[198:201], v[92:95]
	v_mfma_f32_16x16x32_bf16 v[88:91], v[146:149], v[198:201], v[88:91]
	v_mfma_f32_16x16x32_bf16 v[76:79], v[130:133], v[206:209], v[76:79]
	v_mfma_f32_16x16x32_bf16 v[72:75], v[146:149], v[206:209], v[72:75]
	s_setprio 0
	s_setprio 1
	v_mfma_f32_16x16x32_bf16 v[122:125], v[150:153], v[166:169], v[122:125]
	v_mfma_f32_16x16x32_bf16 v[118:121], v[158:161], v[166:169], v[118:121]
	v_mfma_f32_16x16x32_bf16 v[106:109], v[150:153], v[174:177], v[106:109]
	v_mfma_f32_16x16x32_bf16 v[102:105], v[158:161], v[174:177], v[102:105]
	v_mfma_f32_16x16x32_bf16 v[84:87], v[150:153], v[194:197], v[84:87]
	v_mfma_f32_16x16x32_bf16 v[80:83], v[158:161], v[194:197], v[80:83]
	v_mfma_f32_16x16x32_bf16 v[68:71], v[150:153], v[202:205], v[68:71]
	v_mfma_f32_16x16x32_bf16 v[64:67], v[158:161], v[202:205], v[64:67]
	v_mfma_f32_16x16x32_bf16 v[122:125], v[154:157], v[170:173], v[122:125]
	v_mfma_f32_16x16x32_bf16 v[118:121], v[162:165], v[170:173], v[118:121]
	v_mfma_f32_16x16x32_bf16 v[106:109], v[154:157], v[178:181], v[106:109]
	v_mfma_f32_16x16x32_bf16 v[102:105], v[162:165], v[178:181], v[102:105]
	v_mfma_f32_16x16x32_bf16 v[84:87], v[154:157], v[198:201], v[84:87]
	v_mfma_f32_16x16x32_bf16 v[80:83], v[162:165], v[198:201], v[80:83]
	v_mfma_f32_16x16x32_bf16 v[68:71], v[154:157], v[206:209], v[68:71]
	v_mfma_f32_16x16x32_bf16 v[64:67], v[162:165], v[206:209], v[64:67]
	s_setprio 0
	s_barrier
	s_add_i32 s77, s77, s61
	v_lshl_add_u64 v[210:211], s[56:57], 0, v[96:97]
	s_mov_b32 m0, s77
	ds_read_b128 v[166:169], v236 offset:16384
	ds_read_b128 v[170:173], v236 offset:17408
	ds_read_b128 v[174:177], v236 offset:18432
	ds_read_b128 v[178:181], v236 offset:19456
	ds_read_b128 v[194:197], v236 offset:20480
	ds_read_b128 v[198:201], v236 offset:21504
	ds_read_b128 v[202:205], v236 offset:22528
	ds_read_b128 v[206:209], v236 offset:23552
	global_load_lds_dwordx4 v[210:211], off
	s_add_i32 m0, s77, 0x2000
	s_add_u32 s78, s56, 0x80000
	v_lshl_add_u64 v[212:213], s[56:57], 0, v[98:99]
	s_addc_u32 s79, s57, 0
	s_add_i32 s77, s80, s61
	global_load_lds_dwordx4 v[212:213], off
	v_lshl_add_u64 v[214:215], s[78:79], 0, v[96:97]
	s_mov_b32 m0, s77
	v_lshl_add_u64 v[216:217], s[58:59], 0, v[186:187]
	global_load_lds_dwordx4 v[214:215], off
	v_lshl_add_u64 v[214:215], s[78:79], 0, v[98:99]
	s_add_i32 m0, s77, 0x2000
	s_nop 0
	global_load_lds_dwordx4 v[214:215], off
	v_lshl_add_u64 v[214:215], s[58:59], 0, v[188:189]
	s_mov_b32 m0, s62
	s_nop 0
	global_load_lds_dwordx4 v[214:215], off
	s_mov_b32 m0, s63
	s_nop 0
	global_load_lds_dwordx4 v[216:217], off
	s_waitcnt vmcnt(8)
	s_waitcnt lgkmcnt(0)
	s_barrier
; #define PG8_STAGE(bufoff, gbase, voff) do { _Pragma("unroll") for (int _i = 0; _i < 2; ++_i) \
;         __builtin_amdgcn_global_load_lds((const unsigned*)((const char*)(gbase) + (voff)[_i]), (PG8_LAS unsigned*)(lds + (bufoff) + ldsw + _i * 8192), 16, 0, 0); } while (0)
; #define PG8_LDA(dst, b, h) do { _Pragma("unroll") for (int m = 0; m < 4; ++m) _Pragma("unroll") for (int k = 0; k < 2; ++k) dst[m][k] = *(const PG8_LAS bf16x8*)(lds + PG8_SA(b, h) + aoff + m * 2048 + k * 1024); } while (0)
; #define PG8_LDB(dst, b, h) do { _Pragma("unroll") for (int n = 0; n < 2; ++n) _Pragma("unroll") for (int k = 0; k < 2; ++k) dst[n][k] = *(const PG8_LAS bf16x8*)(lds + PG8_SB(b, h) + boff + n * 2048 + k * 1024); } while (0)
; #define PG8_MMA(ai, bj, At, Bt) do { __builtin_amdgcn_s_setprio(1); _Pragma("unroll") for (int m = 0; m < 4; ++m) _Pragma("unroll") for (int n = 0; n < 2; ++n) _Pragma("unroll") for (int k = 0; k < 2; ++k) \
;         acc[ai][bj][m][n] = __builtin_amdgcn_mfma_f32_16x16x32_bf16(Bt[n][k], At[m][k], acc[ai][bj][m][n], 0, 0, 0); __builtin_amdgcn_s_setprio(0); } while (0)
; #define PG8_WAIT_V(n) asm volatile("s_waitcnt vmcnt(" #n ")" ::: "memory")
; #define PG8_WAIT_L(n) asm volatile("s_waitcnt lgkmcnt(" #n ")" ::: "memory")
; template <class Epi, class Sched, bool ALIGN_EPI = false, bool SP2 = false>
; __device__ __forceinline__ void gemm_phase(PG8_LAS unsigned char* lds, const Gemm g, const Sched& S, const Epi& E, const int tid) {
;     ...
;             PG8_WAIT_V(8); PG8_WAIT_L(0); PG8_BAR; PG8_MMA(0, 0, At, B0); PG8_MMA(0, 1, At, B1); PG8_BAR; PG8_SCHED;
;             PG8_LDA(At, 0, 1); PG8_STAGE(PG8_SB(0, 0), b2, voffB); PG8_STAGE(PG8_SB(0, 1), b2 + hstep, voffB); PG8_STAGE(PG8_SA(0, 0), a2, voffA);
;             PG8_WAIT_V(8); PG8_WAIT_L(0); PG8_BAR; PG8_MMA(1, 0, At, B0); PG8_MMA(1, 1, At, B1); PG8_BAR; PG8_SCHED;
;             PG8_LDB(B0, 1, 0); PG8_LDB(B1, 1, 1); PG8_SCHED; PG8_LDA(At, 1, 0); PG8_STAGE(PG8_SA(0, 1), a2 + hstep, voffA);
;             PG8_WAIT_V(8); PG8_WAIT_L(0); PG8_BAR; PG8_MMA(0, 0, At, B0); PG8_MMA(0, 1, At, B1); PG8_BAR; PG8_SCHED;
;             PG8_LDA(At, 1, 1); PG8_STAGE(PG8_SB(1, 0), b3, voffB); PG8_STAGE(PG8_SB(1, 1), b3 + hstep, voffB); PG8_STAGE(PG8_SA(1, 0), a3, voffA);
;             PG8_WAIT_V(8); PG8_WAIT_L(0); PG8_BAR; PG8_MMA(1, 0, At, B0); PG8_MMA(1, 1, At, B1); PG8_BAR; PG8_SCHED;
	s_setprio 1
	s_waitcnt lgkmcnt(0)
	v_mfma_f32_16x16x32_bf16 v[60:63], v[126:129], v[166:169], v[60:63]
	v_mfma_f32_16x16x32_bf16 v[56:59], v[142:145], v[166:169], v[56:59]
	v_mfma_f32_16x16x32_bf16 v[44:47], v[126:129], v[174:177], v[44:47]
	v_mfma_f32_16x16x32_bf16 v[40:43], v[142:145], v[174:177], v[40:43]
	v_mfma_f32_16x16x32_bf16 v[28:31], v[126:129], v[194:197], v[28:31]
	v_mfma_f32_16x16x32_bf16 v[24:27], v[142:145], v[194:197], v[24:27]
	v_mfma_f32_16x16x32_bf16 v[12:15], v[126:129], v[202:205], v[12:15]
	v_mfma_f32_16x16x32_bf16 v[8:11], v[142:145], v[202:205], v[8:11]
	v_mfma_f32_16x16x32_bf16 v[60:63], v[130:133], v[170:173], v[60:63]
	v_mfma_f32_16x16x32_bf16 v[56:59], v[146:149], v[170:173], v[56:59]
	v_mfma_f32_16x16x32_bf16 v[44:47], v[130:133], v[178:181], v[44:47]
	v_mfma_f32_16x16x32_bf16 v[40:43], v[146:149], v[178:181], v[40:43]
	v_mfma_f32_16x16x32_bf16 v[28:31], v[130:133], v[198:201], v[28:31]
	v_mfma_f32_16x16x32_bf16 v[24:27], v[146:149], v[198:201], v[24:27]
	v_mfma_f32_16x16x32_bf16 v[12:15], v[130:133], v[206:209], v[12:15]
	v_mfma_f32_16x16x32_bf16 v[8:11], v[146:149], v[206:209], v[8:11]
	s_setprio 0
	s_setprio 1
	v_mfma_f32_16x16x32_bf16 v[52:55], v[150:153], v[166:169], v[52:55]
	v_mfma_f32_16x16x32_bf16 v[48:51], v[158:161], v[166:169], v[48:51]
	v_mfma_f32_16x16x32_bf16 v[36:39], v[150:153], v[174:177], v[36:39]
	v_mfma_f32_16x16x32_bf16 v[32:35], v[158:161], v[174:177], v[32:35]
	v_mfma_f32_16x16x32_bf16 v[20:23], v[150:153], v[194:197], v[20:23]
	v_mfma_f32_16x16x32_bf16 v[16:19], v[158:161], v[194:197], v[16:19]
	v_mfma_f32_16x16x32_bf16 v[4:7], v[150:153], v[202:205], v[4:7]
	v_mfma_f32_16x16x32_bf16 v[0:3], v[158:161], v[202:205], v[0:3]
	v_mfma_f32_16x16x32_bf16 v[52:55], v[154:157], v[170:173], v[52:55]
	v_mfma_f32_16x16x32_bf16 v[48:51], v[162:165], v[170:173], v[48:51]
	v_mfma_f32_16x16x32_bf16 v[36:39], v[154:157], v[178:181], v[36:39]
	v_mfma_f32_16x16x32_bf16 v[32:35], v[162:165], v[178:181], v[32:35]
	v_mfma_f32_16x16x32_bf16 v[20:23], v[154:157], v[198:201], v[20:23]
	v_mfma_f32_16x16x32_bf16 v[16:19], v[162:165], v[198:201], v[16:19]
	v_mfma_f32_16x16x32_bf16 v[4:7], v[154:157], v[206:209], v[4:7]
	v_mfma_f32_16x16x32_bf16 v[0:3], v[162:165], v[206:209], v[0:3]
	s_setprio 0
	s_barrier
	s_add_i32 s77, 0, 0x18000
	s_add_i32 s78, 0, 0x1c000
	v_add_u32_e32 v146, s77, v233
	v_add_u32_e32 v162, s78, v233
	ds_read_b128 v[126:129], v146
	ds_read_b128 v[130:133], v146 offset:1024
	ds_read_b128 v[142:145], v146 offset:2048
	ds_read_b128 v[146:149], v146 offset:3072
	ds_read_b128 v[150:153], v162
	ds_read_b128 v[154:157], v162 offset:1024
	ds_read_b128 v[158:161], v162 offset:2048
	ds_read_b128 v[162:165], v162 offset:3072
	s_add_u32 s58, s58, 0x80000
	s_addc_u32 s59, s59, 0
	s_mov_b32 m0, s64
	v_lshl_add_u64 v[218:219], s[58:59], 0, v[188:189]
	ds_read_b128 v[166:169], v236 offset:32768
	ds_read_b128 v[170:173], v236 offset:33792
	ds_read_b128 v[174:177], v236 offset:34816
	ds_read_b128 v[178:181], v236 offset:35840
	ds_read_b128 v[194:197], v236 offset:36864
	ds_read_b128 v[198:201], v236 offset:37888
	ds_read_b128 v[202:205], v236 offset:38912
	ds_read_b128 v[206:209], v236 offset:39936
	global_load_lds_dwordx4 v[218:219], off
	v_lshl_add_u64 v[218:219], s[58:59], 0, v[186:187]
	s_mov_b32 m0, s65
	s_nop 0
	global_load_lds_dwordx4 v[218:219], off
	s_waitcnt vmcnt(8)
	s_waitcnt lgkmcnt(0)
	s_barrier
	s_setprio 1
	s_waitcnt lgkmcnt(0)
	v_mfma_f32_16x16x32_bf16 v[138:141], v[126:129], v[166:169], v[138:141]
	v_mfma_f32_16x16x32_bf16 v[134:137], v[142:145], v[166:169], v[134:137]
	v_mfma_f32_16x16x32_bf16 v[114:117], v[126:129], v[174:177], v[114:117]
	v_mfma_f32_16x16x32_bf16 v[110:113], v[142:145], v[174:177], v[110:113]
	v_mfma_f32_16x16x32_bf16 v[92:95], v[126:129], v[194:197], v[92:95]
	v_mfma_f32_16x16x32_bf16 v[88:91], v[142:145], v[194:197], v[88:91]
	v_mfma_f32_16x16x32_bf16 v[76:79], v[126:129], v[202:205], v[76:79]
	v_mfma_f32_16x16x32_bf16 v[72:75], v[142:145], v[202:205], v[72:75]
	v_mfma_f32_16x16x32_bf16 v[138:141], v[130:133], v[170:173], v[138:141]
	v_mfma_f32_16x16x32_bf16 v[134:137], v[146:149], v[170:173], v[134:137]
	v_mfma_f32_16x16x32_bf16 v[114:117], v[130:133], v[178:181], v[114:117]
	v_mfma_f32_16x16x32_bf16 v[110:113], v[146:149], v[178:181], v[110:113]
	v_mfma_f32_16x16x32_bf16 v[92:95], v[130:133], v[198:201], v[92:95]
	v_mfma_f32_16x16x32_bf16 v[88:91], v[146:149], v[198:201], v[88:91]
	v_mfma_f32_16x16x32_bf16 v[76:79], v[130:133], v[206:209], v[76:79]
	v_mfma_f32_16x16x32_bf16 v[72:75], v[146:149], v[206:209], v[72:75]
	s_setprio 0
	s_setprio 1
	v_mfma_f32_16x16x32_bf16 v[122:125], v[150:153], v[166:169], v[122:125]
	v_mfma_f32_16x16x32_bf16 v[118:121], v[158:161], v[166:169], v[118:121]
	v_mfma_f32_16x16x32_bf16 v[106:109], v[150:153], v[174:177], v[106:109]
	v_mfma_f32_16x16x32_bf16 v[102:105], v[158:161], v[174:177], v[102:105]
	v_mfma_f32_16x16x32_bf16 v[84:87], v[150:153], v[194:197], v[84:87]
	v_mfma_f32_16x16x32_bf16 v[80:83], v[158:161], v[194:197], v[80:83]
	v_mfma_f32_16x16x32_bf16 v[68:71], v[150:153], v[202:205], v[68:71]
	v_mfma_f32_16x16x32_bf16 v[64:67], v[158:161], v[202:205], v[64:67]
	v_mfma_f32_16x16x32_bf16 v[122:125], v[154:157], v[170:173], v[122:125]
	v_mfma_f32_16x16x32_bf16 v[118:121], v[162:165], v[170:173], v[118:121]
	v_mfma_f32_16x16x32_bf16 v[106:109], v[154:157], v[178:181], v[106:109]
	v_mfma_f32_16x16x32_bf16 v[102:105], v[162:165], v[178:181], v[102:105]
	v_mfma_f32_16x16x32_bf16 v[84:87], v[154:157], v[198:201], v[84:87]
	v_mfma_f32_16x16x32_bf16 v[80:83], v[162:165], v[198:201], v[80:83]
	v_mfma_f32_16x16x32_bf16 v[68:71], v[154:157], v[206:209], v[68:71]
	v_mfma_f32_16x16x32_bf16 v[64:67], v[162:165], v[206:209], v[64:67]
	s_setprio 0
	s_barrier
; #define PG8_WAIT_V(n) asm volatile("s_waitcnt vmcnt(" #n ")" ::: "memory")
; #define PG8_BAR __builtin_amdgcn_s_barrier()
;     __device__ __forceinline__ void operator()(const f32x4 (&acc)[2][2][4][2], const Unit& u, int wr, int wc, int fr, int fq) const {
;         const int row0 = u.pm * BM + wr * 64 + fr, col0 = u.pn * BM + wc * 32 + 8 * fq, lcol = u.pn * BM + (wc * 4 + fq) * 16;
; #pragma unroll
;         for (int ai = 0; ai < 2; ++ai) {
;             u32x4 L4[4], H4[4][2];
; #pragma unroll
;             for (int m = 0; m < 4; ++m) {
;                 const int row = row0 + ai * HALF + m * 16; const size_t off = (size_t)row * 2048 + col0, loff = (size_t)row * 2048 + lcol;
; template <class Epi, class Sched, bool ALIGN_EPI = false, bool SP2 = false>
; __device__ __forceinline__ void gemm_phase(PG8_LAS unsigned char* lds, const Gemm g, const Sched& S, const Epi& E, const int tid) {
;     ...
;         for (int t = 0; t < nt; t += 2) {
;             const bool last = (t == nt - 2);
;             const char* a1 = cA + (size_t)(t + 1) * kstep;
;             const char* a2 = last ? nA : cA + (size_t)(t + 2) * kstep; const char* b2 = last ? nB : cB + (size_t)(t + 2) * kstep;
;             const char* a3 = a2 + kstep; const char* b3 = b2 + kstep;
;             if (last && has_next) S.a_ready(nxt);
;             if constexpr (SP2) {
;             PG8_LDB(B0, 0, 0); PG8_LDB(B1, 0, 1); PG8_SCHED; PG8_LDA(At, 0, 0); PG8_STAGE(PG8_SA(1, 1), a1 + hstep, voffA);
;             PG8_WAIT_V(8); PG8_WAIT_L(0); PG8_BAR; PG8_MMA(0, 0, At, B0); PG8_MMA(0, 1, At, B1); PG8_BAR; PG8_SCHED;
;             PG8_LDA(At, 0, 1); PG8_STAGE(PG8_SB(0, 0), b2, voffB); PG8_STAGE(PG8_SB(0, 1), b2 + hstep, voffB); PG8_STAGE(PG8_SA(0, 0), a2, voffA);
;             PG8_WAIT_V(8); PG8_WAIT_L(0); PG8_BAR; PG8_MMA(1, 0, At, B0); PG8_MMA(1, 1, At, B1); PG8_BAR; PG8_SCHED;
;             PG8_LDB(B0, 1, 0); PG8_LDB(B1, 1, 1); PG8_SCHED; PG8_LDA(At, 1, 0); PG8_STAGE(PG8_SA(0, 1), a2 + hstep, voffA);
;             PG8_WAIT_V(8); PG8_WAIT_L(0); PG8_BAR; PG8_MMA(0, 0, At, B0); PG8_MMA(0, 1, At, B1); PG8_BAR; PG8_SCHED;
;             PG8_LDA(At, 1, 1); PG8_STAGE(PG8_SB(1, 0), b3, voffB); PG8_STAGE(PG8_SB(1, 1), b3 + hstep, voffB); PG8_STAGE(PG8_SA(1, 0), a3, voffA);
;             PG8_WAIT_V(8); PG8_WAIT_L(0); PG8_BAR; PG8_MMA(1, 0, At, B0); PG8_MMA(1, 1, At, B1); PG8_BAR; PG8_SCHED;
	s_add_i32 s58, s77, s61
	v_lshl_add_u64 v[210:211], v[210:211], 0, s[28:29]
	s_mov_b32 m0, s58
	ds_read_b128 v[166:169], v236 offset:49152
	ds_read_b128 v[170:173], v236 offset:50176
	ds_read_b128 v[174:177], v236 offset:51200
	ds_read_b128 v[178:181], v236 offset:52224
	ds_read_b128 v[194:197], v236 offset:53248
	ds_read_b128 v[198:201], v236 offset:54272
	ds_read_b128 v[202:205], v236 offset:55296
	ds_read_b128 v[206:209], v236 offset:56320
	global_load_lds_dwordx4 v[210:211], off
	s_add_i32 m0, s58, 0x2000
	s_add_u32 s56, s56, 0x80080
	v_lshl_add_u64 v[210:211], v[212:213], 0, s[28:29]
	s_addc_u32 s57, s57, 0
	s_add_i32 s58, s78, s61
	global_load_lds_dwordx4 v[210:211], off
	v_lshl_add_u64 v[210:211], s[56:57], 0, v[96:97]
	s_mov_b32 m0, s58
	s_nop 0
	global_load_lds_dwordx4 v[210:211], off
	v_lshl_add_u64 v[210:211], s[56:57], 0, v[98:99]
	s_add_i32 m0, s58, 0x2000
	s_nop 0
	global_load_lds_dwordx4 v[210:211], off
	v_lshl_add_u64 v[210:211], v[214:215], 0, s[28:29]
	s_mov_b32 m0, s66
	s_nop 0
	global_load_lds_dwordx4 v[210:211], off
	v_lshl_add_u64 v[210:211], v[216:217], 0, s[28:29]
	s_mov_b32 m0, s67
	s_nop 0
	global_load_lds_dwordx4 v[210:211], off
	s_waitcnt vmcnt(8)
	s_waitcnt lgkmcnt(0)
	s_barrier
	s_setprio 1
	s_waitcnt lgkmcnt(0)
	v_mfma_f32_16x16x32_bf16 v[60:63], v[126:129], v[166:169], v[60:63]
	v_mfma_f32_16x16x32_bf16 v[56:59], v[142:145], v[166:169], v[56:59]
	v_mfma_f32_16x16x32_bf16 v[44:47], v[126:129], v[174:177], v[44:47]
	v_mfma_f32_16x16x32_bf16 v[40:43], v[142:145], v[174:177], v[40:43]
	v_mfma_f32_16x16x32_bf16 v[28:31], v[126:129], v[194:197], v[28:31]
	v_mfma_f32_16x16x32_bf16 v[24:27], v[142:145], v[194:197], v[24:27]
	v_mfma_f32_16x16x32_bf16 v[12:15], v[126:129], v[202:205], v[12:15]
	v_mfma_f32_16x16x32_bf16 v[8:11], v[142:145], v[202:205], v[8:11]
	v_mfma_f32_16x16x32_bf16 v[60:63], v[130:133], v[170:173], v[60:63]
	v_mfma_f32_16x16x32_bf16 v[56:59], v[146:149], v[170:173], v[56:59]
	v_mfma_f32_16x16x32_bf16 v[44:47], v[130:133], v[178:181], v[44:47]
	v_mfma_f32_16x16x32_bf16 v[40:43], v[146:149], v[178:181], v[40:43]
	v_mfma_f32_16x16x32_bf16 v[28:31], v[130:133], v[198:201], v[28:31]
	v_mfma_f32_16x16x32_bf16 v[24:27], v[146:149], v[198:201], v[24:27]
	v_mfma_f32_16x16x32_bf16 v[12:15], v[130:133], v[206:209], v[12:15]
	v_mfma_f32_16x16x32_bf16 v[8:11], v[146:149], v[206:209], v[8:11]
	s_setprio 0
	s_setprio 1
	v_mfma_f32_16x16x32_bf16 v[52:55], v[150:153], v[166:169], v[52:55]
	v_mfma_f32_16x16x32_bf16 v[48:51], v[158:161], v[166:169], v[48:51]
	v_mfma_f32_16x16x32_bf16 v[36:39], v[150:153], v[174:177], v[36:39]
	v_mfma_f32_16x16x32_bf16 v[32:35], v[158:161], v[174:177], v[32:35]
	v_mfma_f32_16x16x32_bf16 v[20:23], v[150:153], v[194:197], v[20:23]
	v_mfma_f32_16x16x32_bf16 v[16:19], v[158:161], v[194:197], v[16:19]
	v_mfma_f32_16x16x32_bf16 v[4:7], v[150:153], v[202:205], v[4:7]
	v_mfma_f32_16x16x32_bf16 v[0:3], v[158:161], v[202:205], v[0:3]
	v_mfma_f32_16x16x32_bf16 v[52:55], v[154:157], v[170:173], v[52:55]
	v_mfma_f32_16x16x32_bf16 v[48:51], v[162:165], v[170:173], v[48:51]
	v_mfma_f32_16x16x32_bf16 v[36:39], v[154:157], v[178:181], v[36:39]
	v_mfma_f32_16x16x32_bf16 v[32:35], v[162:165], v[178:181], v[32:35]
	v_mfma_f32_16x16x32_bf16 v[20:23], v[154:157], v[198:201], v[20:23]
	v_mfma_f32_16x16x32_bf16 v[16:19], v[162:165], v[198:201], v[16:19]
	v_mfma_f32_16x16x32_bf16 v[4:7], v[154:157], v[206:209], v[4:7]
	v_mfma_f32_16x16x32_bf16 v[0:3], v[162:165], v[206:209], v[0:3]
	s_setprio 0
	s_add_i32 s76, s76, 2
	s_add_u32 s73, s73, 0x100
	s_addc_u32 s75, s75, 0
	s_add_u32 s54, s54, 0x100
	s_addc_u32 s55, s55, 0
	s_add_u32 s56, s54, 0xfff80080
	s_addc_u32 s57, s55, -1
	s_add_i32 s77, 0, 0x10000
	s_cmp_eq_u32 s76, 28
	s_cselect_b32 s59, s49, s57
	s_cselect_b32 s58, s71, s56
	s_cselect_b32 s57, s47, s75
	s_cselect_b32 s56, s72, s73
	s_add_i32 s80, 0, 0x14000
	s_cmp_gt_u32 s76, 29
	s_barrier
	s_cbranch_scc0 .Lrot0_1199
	v_and_b32_e32 v127, 64, v228
	v_xor_b32_e32 v126, 16, v228
	v_add_u32_e32 v127, 64, v127
	v_cmp_lt_i32_e32 vcc, v126, v127
	s_lshl_b32 s47, s69, 8
	v_lshl_add_u32 v198, s70, 8, v101
	v_cndmask_b32_e32 v126, v228, v126, vcc
	v_or_b32_e32 v194, s47, v235
	v_lshlrev_b32_e32 v238, 2, v126
	v_xor_b32_e32 v126, 32, v228
	v_or_b32_e32 v196, s47, v234
	v_ashrrev_i32_e32 v195, 31, v194
	v_cmp_lt_i32_e32 vcc, v126, v127
	v_ashrrev_i32_e32 v199, 31, v198
	v_ashrrev_i32_e32 v197, 31, v196
	v_cndmask_b32_e32 v126, v228, v126, vcc
	v_lshl_add_u64 v[202:203], s[34:35], 0, v[194:195]
	v_lshlrev_b64 v[216:217], 11, v[198:199]
	v_lshlrev_b32_e32 v237, 2, v126
	v_lshlrev_b64 v[218:219], 1, v[196:197]
	v_lshl_add_u64 v[126:127], v[202:203], 0, v[216:217]
	v_lshl_add_u64 v[200:201], s[30:31], 0, v[218:219]
	global_load_dwordx4 v[170:173], v[126:127], off
	v_lshlrev_b64 v[220:221], 12, v[198:199]
	v_lshl_add_u64 v[126:127], v[200:201], 0, v[220:221]
	global_load_dwordx4 v[178:181], v[126:127], off
	global_load_dwordx4 v[174:177], v[126:127], off offset:256
	v_or_b32_e32 v212, 16, v198
	v_ashrrev_i32_e32 v213, 31, v212
	v_lshlrev_b64 v[214:215], 11, v[212:213]
	v_lshl_add_u64 v[126:127], v[202:203], 0, v[214:215]
	v_or_b32_e32 v208, 32, v198
	global_load_dwordx4 v[158:161], v[126:127], off
	v_lshlrev_b64 v[126:127], 12, v[212:213]
	v_ashrrev_i32_e32 v209, 31, v208
	v_lshl_add_u64 v[126:127], v[200:201], 0, v[126:127]
	v_lshlrev_b64 v[210:211], 11, v[208:209]
	global_load_dwordx4 v[166:169], v[126:127], off
	global_load_dwordx4 v[162:165], v[126:127], off offset:256
	v_lshl_add_u64 v[126:127], v[202:203], 0, v[210:211]
	v_or_b32_e32 v204, 48, v198
	global_load_dwordx4 v[146:149], v[126:127], off
	v_lshlrev_b64 v[126:127], 12, v[208:209]
	v_ashrrev_i32_e32 v205, 31, v204
	v_lshl_add_u64 v[126:127], v[200:201], 0, v[126:127]
	v_lshlrev_b64 v[206:207], 11, v[204:205]
	v_lshlrev_b64 v[130:131], 12, v[204:205]
	global_load_dwordx4 v[154:157], v[126:127], off
	global_load_dwordx4 v[150:153], v[126:127], off offset:256
	v_lshl_add_u64 v[126:127], v[202:203], 0, v[206:207]
	v_lshl_add_u64 v[130:131], v[200:201], 0, v[130:131]
	global_load_dwordx4 v[126:129], v[126:127], off
	s_nop 0
	global_load_dwordx4 v[142:145], v[130:131], off
	s_nop 0
	global_load_dwordx4 v[130:133], v[130:131], off offset:256
	v_mov_b32_e32 v225, v134
	v_mov_b32_e32 v243, v136
	v_mov_b32_e32 v242, v140
	s_waitcnt vmcnt(0)
; #define PG8_GAS __attribute__((address_space(1)))
; __device__ __forceinline__ float e_x24(unsigned h16, unsigned l8) { return __uint_as_float(((h16 - (l8 >> 7)) << 16) | (l8 << 8)); }
;     __device__ __forceinline__ void operator()(const f32x4 (&acc)[2][2][4][2], const Unit& u, int wr, int wc, int fr, int fq) const {
;     ...
;                 for (int bj = 0; bj < 2; ++bj) {
;                     const u32x4 h4 = H4[m][bj];
;                     u32x4 ho;
; #pragma unroll
;                     for (int j = 0; j < 4; ++j) {
;                         const unsigned lw = l4[2 * bj + (j >> 1)], lb0 = (lw >> (16 * (j & 1))) & 0xffu, lb1 = (lw >> (16 * (j & 1) + 8)) & 0xffu;
;                         const float x0 = e_x24(h4[j] & 0xffffu, lb0) + acc[ai][bj][m][j >> 1][2 * (j & 1)] * scale, x1 = e_x24(h4[j] >> 16, lb1) + acc[ai][bj][m][j >> 1][2 * (j & 1) + 1] * scale;
;                         const unsigned b0 = __float_as_uint(x0), b1 = __float_as_uint(x1);
;                         ho[j] = ((b0 + 0x8000u) >> 16) | ((b1 + 0x8000u) & 0xffff0000u);
;                         const unsigned nb = ((b0 >> 8) & 0xffu) | (b1 & 0xff00u);
;                         if ((j & 1) == 0) lo4[2 * bj + (j >> 1)] = nb; else lo4[2 * bj + (j >> 1)] |= nb << 16;
;                         ss += x0 * x0 + x1 * x1;
;                     }
;                     *(PG8_GAS u32x4*)(hout + off + bj * HALF) = ho;
;                 }
	v_lshrrev_b32_sdwa v182, v229, v171 dst_sel:DWORD dst_unused:UNUSED_PAD src0_sel:DWORD src1_sel:BYTE_0
	v_lshrrev_b32_sdwa v183, v229, v170 dst_sel:DWORD dst_unused:UNUSED_PAD src0_sel:DWORD src1_sel:BYTE_0
	v_sub_u32_sdwa v183, v178, v183 dst_sel:WORD_1 dst_unused:UNUSED_PAD src0_sel:DWORD src1_sel:DWORD
	v_sub_u32_sdwa v182, v180, v182 dst_sel:WORD_1 dst_unused:UNUSED_PAD src0_sel:DWORD src1_sel:DWORD
	v_lshlrev_b32_sdwa v222, v230, v171 dst_sel:DWORD dst_unused:UNUSED_PAD src0_sel:DWORD src1_sel:BYTE_0
	v_lshlrev_b32_sdwa v224, v230, v170 dst_sel:DWORD dst_unused:UNUSED_PAD src0_sel:DWORD src1_sel:BYTE_0
	v_or_b32_e32 v223, v182, v222
	v_or_b32_e32 v222, v183, v224
	v_mov_b32_e32 v224, v138
	v_pk_add_f32 v[222:223], v[224:225], v[222:223]
	v_lshlrev_b32_e32 v182, 1, v170
	v_add_u32_e32 v134, 0x8000, v222
	v_lshrrev_b32_e32 v138, 16, v134
	v_lshlrev_b32_e32 v134, 1, v171
	v_and_b32_e32 v134, 0x10000, v134
	v_and_b32_e32 v182, 0x10000, v182
	v_sub_u32_e32 v134, v180, v134
	v_sub_u32_e32 v178, v178, v182
	v_and_b32_e32 v134, 0xffff0000, v134
	v_and_b32_e32 v178, 0xffff0000, v178
	v_and_b32_e32 v180, 0xff00, v171
	v_and_b32_e32 v182, 0xff00, v170
	v_or_b32_e32 v225, v134, v180
	v_or_b32_e32 v224, v178, v182
	v_mov_b32_e32 v134, v139
	v_pk_add_f32 v[224:225], v[134:135], v[224:225]
	v_and_b32_sdwa v135, v171, s93 dst_sel:DWORD dst_unused:UNUSED_PAD src0_sel:WORD_1 src1_sel:DWORD
	v_and_b32_sdwa v178, v170, s93 dst_sel:DWORD dst_unused:UNUSED_PAD src0_sel:WORD_1 src1_sel:DWORD
	v_lshlrev_b32_sdwa v182, v231, v170 dst_sel:DWORD dst_unused:UNUSED_PAD src0_sel:DWORD src1_sel:BYTE_3
	v_lshlrev_b32_sdwa v136, v231, v171 dst_sel:DWORD dst_unused:UNUSED_PAD src0_sel:DWORD src1_sel:BYTE_3
	v_lshrrev_b32_e32 v180, 7, v178
	v_lshrrev_b32_e32 v183, 7, v135
	v_and_b32_e32 v136, 0x10000, v136
	v_and_b32_e32 v140, 0x10000, v182
	v_sub_u32_sdwa v180, v179, v180 dst_sel:WORD_1 dst_unused:UNUSED_PAD src0_sel:DWORD src1_sel:DWORD
	v_sub_u32_sdwa v183, v181, v183 dst_sel:WORD_1 dst_unused:UNUSED_PAD src0_sel:DWORD src1_sel:DWORD
	v_lshlrev_b32_e32 v135, 8, v135
	v_lshlrev_b32_e32 v178, 8, v178
	v_sub_u32_e32 v136, v181, v136
	v_sub_u32_e32 v140, v179, v140
	v_or_b32_e32 v241, v183, v135
	v_or_b32_e32 v240, v180, v178
	v_and_b32_e32 v136, 0xffff0000, v136
	v_and_b32_e32 v140, 0xffff0000, v140
	v_lshlrev_b32_sdwa v171, v230, v171 dst_sel:DWORD dst_unused:UNUSED_PAD src0_sel:DWORD src1_sel:BYTE_3
	v_lshlrev_b32_sdwa v170, v230, v170 dst_sel:DWORD dst_unused:UNUSED_PAD src0_sel:DWORD src1_sel:BYTE_3
	v_pk_add_f32 v[240:241], v[242:243], v[240:241]
	v_or_b32_e32 v171, v136, v171
	v_or_b32_e32 v170, v140, v170
	v_mov_b32_e32 v136, v141
	v_add_u32_e32 v135, 0x8000, v240
	v_pk_add_f32 v[140:141], v[136:137], v[170:171]
	v_lshrrev_b32_e32 v135, 16, v135
	v_add_u32_e32 v136, 0x8000, v140
	v_and_or_b32 v135, v136, s90, v135
	v_pk_mul_f32 v[136:137], v[140:141], v[140:141]
	v_add_u32_e32 v178, 0x8000, v141
	v_pk_fma_f32 v[170:171], v[240:241], v[240:241], v[136:137]
	v_add_u32_e32 v136, 0x8000, v223
	v_lshrrev_b32_e32 v136, 16, v136
	v_add_u32_e32 v137, 0x8000, v225
	v_and_or_b32 v136, v137, s90, v136
	v_add_u32_e32 v137, 0x8000, v241
	v_lshrrev_b32_e32 v137, 16, v137
	v_add_u32_e32 v134, 0x8000, v224
	v_and_or_b32 v137, v178, s90, v137
	v_lshl_add_u64 v[178:179], s[30:31], 0, v[220:221]
	v_and_or_b32 v134, v134, s90, v138
	v_lshl_add_u64 v[178:179], v[178:179], 0, v[218:219]
	global_store_dwordx4 v[178:179], v[134:137], off
	v_lshlrev_b32_sdwa v182, v231, v172 dst_sel:DWORD dst_unused:UNUSED_PAD src0_sel:DWORD src1_sel:BYTE_3
	v_mov_b32_e32 v219, v120
	v_lshrrev_b32_sdwa v134, v229, v173 dst_sel:DWORD dst_unused:UNUSED_PAD src0_sel:DWORD src1_sel:BYTE_0
	v_lshrrev_b32_sdwa v135, v229, v172 dst_sel:DWORD dst_unused:UNUSED_PAD src0_sel:DWORD src1_sel:BYTE_0
	v_sub_u32_sdwa v136, v174, v135 dst_sel:WORD_1 dst_unused:UNUSED_PAD src0_sel:DWORD src1_sel:DWORD
	v_sub_u32_sdwa v134, v176, v134 dst_sel:WORD_1 dst_unused:UNUSED_PAD src0_sel:DWORD src1_sel:DWORD
	v_lshlrev_b32_sdwa v135, v230, v173 dst_sel:DWORD dst_unused:UNUSED_PAD src0_sel:DWORD src1_sel:BYTE_0
	v_lshlrev_b32_sdwa v137, v230, v172 dst_sel:DWORD dst_unused:UNUSED_PAD src0_sel:DWORD src1_sel:BYTE_0
	v_or_b32_e32 v135, v134, v135
	v_or_b32_e32 v134, v136, v137
	v_mov_b32_e32 v136, v122
	v_mov_b32_e32 v137, v118
	v_pk_add_f32 v[134:135], v[136:137], v[134:135]
	v_lshlrev_b32_e32 v122, 1, v172
; #define PG8_GAS __attribute__((address_space(1)))
; __device__ __forceinline__ float e_x24(unsigned h16, unsigned l8) { return __uint_as_float(((h16 - (l8 >> 7)) << 16) | (l8 << 8)); }
;     __device__ __forceinline__ void operator()(const f32x4 (&acc)[2][2][4][2], const Unit& u, int wr, int wc, int fr, int fq) const {
;     ...
;                 for (int bj = 0; bj < 2; ++bj) {
;                     const u32x4 h4 = H4[m][bj];
;                     u32x4 ho;
; #pragma unroll
;                     for (int j = 0; j < 4; ++j) {
;                         const unsigned lw = l4[2 * bj + (j >> 1)], lb0 = (lw >> (16 * (j & 1))) & 0xffu, lb1 = (lw >> (16 * (j & 1) + 8)) & 0xffu;
;                         const float x0 = e_x24(h4[j] & 0xffffu, lb0) + acc[ai][bj][m][j >> 1][2 * (j & 1)] * scale, x1 = e_x24(h4[j] >> 16, lb1) + acc[ai][bj][m][j >> 1][2 * (j & 1) + 1] * scale;
;                         const unsigned b0 = __float_as_uint(x0), b1 = __float_as_uint(x1);
;                         ho[j] = ((b0 + 0x8000u) >> 16) | ((b1 + 0x8000u) & 0xffff0000u);
;                         const unsigned nb = ((b0 >> 8) & 0xffu) | (b1 & 0xff00u);
;                         if ((j & 1) == 0) lo4[2 * bj + (j >> 1)] = nb; else lo4[2 * bj + (j >> 1)] |= nb << 16;
;                         ss += x0 * x0 + x1 * x1;
;                     }
;                     *(PG8_GAS u32x4*)(hout + off + bj * HALF) = ho;
;                 }
;                 *(PG8_GAS u32x4*)(lout + loff) = lo4;
;                 ss += __shfl_xor(ss, 16); ss += __shfl_xor(ss, 32);
;                 if (fq == 0) __hip_atomic_fetch_add((PG8_GAS unsigned long long*)(rowsq_out + row), (unsigned long long)(ss * 16777216.0f + 0.5f), __ATOMIC_RELAXED, __HIP_MEMORY_SCOPE_AGENT);
	v_add_u32_e32 v118, 0x8000, v134
	v_lshrrev_b32_e32 v180, 16, v118
	v_lshlrev_b32_e32 v118, 1, v173
	v_and_b32_e32 v118, 0x10000, v118
	v_and_b32_e32 v122, 0x10000, v122
	v_sub_u32_e32 v118, v176, v118
	v_sub_u32_e32 v122, v174, v122
	v_and_b32_e32 v118, 0xffff0000, v118
	v_and_b32_e32 v122, 0xffff0000, v122
	v_and_b32_e32 v136, 0xff00, v173
	v_and_b32_e32 v174, 0xff00, v172
	v_or_b32_e32 v137, v118, v136
	v_or_b32_e32 v136, v122, v174
	v_mov_b32_e32 v118, v123
	v_pk_add_f32 v[122:123], v[118:119], v[136:137]
	v_and_b32_sdwa v119, v173, s93 dst_sel:DWORD dst_unused:UNUSED_PAD src0_sel:WORD_1 src1_sel:DWORD
	v_add_u32_e32 v118, 0x8000, v122
	v_and_b32_sdwa v174, v172, s93 dst_sel:DWORD dst_unused:UNUSED_PAD src0_sel:WORD_1 src1_sel:DWORD
	v_lshlrev_b32_sdwa v120, v231, v173 dst_sel:DWORD dst_unused:UNUSED_PAD src0_sel:DWORD src1_sel:BYTE_3
	v_and_or_b32 v118, v118, s90, v180
	v_lshrrev_b32_e32 v176, 7, v174
	v_lshrrev_b32_e32 v180, 7, v119
	v_mov_b32_e32 v218, v124
	v_and_b32_e32 v120, 0x10000, v120
	v_and_b32_e32 v124, 0x10000, v182
	v_sub_u32_sdwa v176, v175, v176 dst_sel:WORD_1 dst_unused:UNUSED_PAD src0_sel:DWORD src1_sel:DWORD
	v_sub_u32_sdwa v180, v177, v180 dst_sel:WORD_1 dst_unused:UNUSED_PAD src0_sel:DWORD src1_sel:DWORD
	v_lshlrev_b32_e32 v119, 8, v119
	v_lshlrev_b32_e32 v174, 8, v174
	v_sub_u32_e32 v120, v177, v120
	v_sub_u32_e32 v124, v175, v124
	v_or_b32_e32 v181, v180, v119
	v_or_b32_e32 v180, v176, v174
	v_and_b32_e32 v120, 0xffff0000, v120
	v_and_b32_e32 v124, 0xffff0000, v124
	v_lshlrev_b32_sdwa v173, v230, v173 dst_sel:DWORD dst_unused:UNUSED_PAD src0_sel:DWORD src1_sel:BYTE_3
	v_lshlrev_b32_sdwa v172, v230, v172 dst_sel:DWORD dst_unused:UNUSED_PAD src0_sel:DWORD src1_sel:BYTE_3
	v_pk_add_f32 v[180:181], v[218:219], v[180:181]
	v_or_b32_e32 v173, v120, v173
	v_or_b32_e32 v172, v124, v172
	v_mov_b32_e32 v120, v125
	v_add_u32_e32 v119, 0x8000, v180
	v_pk_add_f32 v[124:125], v[120:121], v[172:173]
	v_lshrrev_b32_e32 v119, 16, v119
	v_add_u32_e32 v120, 0x8000, v124
	v_pk_mul_f32 v[138:139], v[224:225], v[224:225]
	v_pk_mul_f32 v[136:137], v[122:123], v[122:123]
	v_and_or_b32 v119, v120, s90, v119
	v_pk_mul_f32 v[120:121], v[124:125], v[124:125]
	v_pk_fma_f32 v[138:139], v[222:223], v[222:223], v[138:139]
	v_pk_fma_f32 v[136:137], v[134:135], v[134:135], v[136:137]
	v_pk_fma_f32 v[172:173], v[180:181], v[180:181], v[120:121]
	v_add_u32_e32 v120, 0x8000, v135
	v_lshrrev_b32_e32 v134, 8, v134
	v_lshrrev_b32_e32 v120, 16, v120
	v_add_u32_e32 v121, 0x8000, v123
	v_perm_b32 v122, v122, v134, s94
	v_add_f32_e32 v134, v138, v170
	v_and_or_b32 v120, v121, s90, v120
	v_add_u32_e32 v121, 0x8000, v181
	v_add_f32_e32 v134, v139, v134
	v_lshrrev_b32_e32 v121, 16, v121
	v_add_u32_e32 v174, 0x8000, v125
	v_add_f32_e32 v134, v171, v134
	v_and_or_b32 v121, v174, s90, v121
	v_lshrrev_b32_e32 v174, 8, v181
	v_lshrrev_b32_e32 v175, 8, v180
	v_add_f32_e32 v134, v136, v134
	v_lshrrev_b32_e32 v176, 8, v241
	v_lshrrev_b32_e32 v177, 8, v240
	v_perm_b32 v124, v124, v175, s94
	v_perm_b32 v125, v125, v174, s94
	v_lshrrev_b32_e32 v135, 8, v135
	v_lshrrev_b32_e32 v174, 8, v223
	v_lshrrev_b32_e32 v175, 8, v222
	v_add_f32_e32 v134, v172, v134
	v_perm_b32 v140, v140, v177, s94
	v_perm_b32 v141, v141, v176, s94
	v_perm_b32 v175, v224, v175, s94
	v_perm_b32 v174, v225, v174, s94
	v_perm_b32 v123, v123, v135, s94
	v_add_f32_e32 v134, v137, v134
	global_store_dwordx4 v[178:179], v[118:121], off offset:256
	v_lshl_or_b32 v125, v125, 16, v123
	v_lshl_or_b32 v124, v124, 16, v122
	v_lshl_add_u64 v[118:119], s[34:35], 0, v[216:217]
	v_lshl_or_b32 v123, v141, 16, v174
	v_lshl_or_b32 v122, v140, 16, v175
	v_add_f32_e32 v134, v173, v134
	v_lshl_add_u64 v[118:119], v[118:119], 0, v[194:195]
	global_store_dwordx4 v[118:119], v[122:125], off
	ds_bpermute_b32 v118, v238, v134
	s_waitcnt lgkmcnt(0)
	v_add_f32_e32 v118, v134, v118
	ds_bpermute_b32 v119, v237, v118
	s_and_saveexec_b64 s[54:55], s[40:41]
	s_mov_b32 s80, 0x4b800000
	s_cbranch_execz .LBB0_1202
	s_waitcnt lgkmcnt(0)
	v_add_f32_e32 v118, v118, v119
	v_fma_f32 v118, v118, s80, 0.5
	v_trunc_f32_e32 v118, v118
	v_mul_f32_e32 v119, 0x2f800000, v118
	v_floor_f32_e32 v119, v119
	v_fmac_f32_e32 v118, 0xcf800000, v119
	v_cvt_u32_f32_e32 v118, v118
	v_cvt_u32_f32_e32 v119, v119
	v_lshl_add_u64 v[120:121], v[198:199], 3, s[44:45]
	global_atomic_add_x2 v[120:121], v[118:119], off
